# P6 group-norm loop hand-rewritten (8 items per trip, batched loads); P7 epilogue gate/residual loads batched; half of the workgroups start P7 half a tile later
# speedup vs baseline: 1.0543x; 1.0239x over previous
.LBB0_8:
	v_readlane_b32 s4, v252, 3
	v_readlane_b32 s5, v252, 4
	s_mov_b64 s[4:5], 0
	v_readlane_b32 s6, v252, 5
	v_writelane_b32 v254, s4, 37
	s_mov_b64 s[0:1], -1
	s_cmp_lt_i32 s6, 3
	v_writelane_b32 v254, s5, 38
	v_readlane_b32 s7, v252, 6
	s_cbranch_scc1 .LBB0_235
	v_readlane_b32 s4, v252, 3
	v_readlane_b32 s6, v252, 5
	s_cmp_gt_i32 s6, 3
	v_readlane_b32 s5, v252, 4
	v_readlane_b32 s7, v252, 6
	s_cbranch_scc0 .LBB0_17
	s_cmp_gt_i32 s6, 4
	s_cbranch_scc0 .LBB0_18
	s_cmp_eq_u32 s6, 5
	s_cbranch_scc0 .LBB0_16
	s_mov_b32 s5, s35
	s_mov_b32 s0, s98
	s_mov_b32 s1, -1
	v_mbcnt_lo_u32_b32 v0, -1, 0
	v_readlane_b32 s4, v252, 0
	v_mbcnt_hi_u32_b32 v0, s1, v0
	v_lshl_add_u32 v0, s0, 6, v0
	s_mov_b32 s0, 0x28000
	v_ashrrev_i32_e32 v6, 6, v0
	v_lshl_add_u32 v3, s4, 3, v6
	v_cmp_gt_i32_e32 vcc, s0, v3
	s_and_saveexec_b64 s[0:1], vcc
	s_cbranch_execz .LBB0_15
	v_and_b32_e32 v2, 63, v0
	v_xor_b32_e32 v4, 32, v2
	v_xor_b32_e32 v5, 16, v2
	v_xor_b32_e32 v6, 8, v2
	v_xor_b32_e32 v7, 4, v2
	v_xor_b32_e32 v8, 2, v2
	v_xor_b32_e32 v9, 1, v2
	v_lshlrev_b32_e32 v4, 2, v4
	v_lshlrev_b32_e32 v5, 2, v5
	v_lshlrev_b32_e32 v6, 2, v6
	v_lshlrev_b32_e32 v7, 2, v7
	v_lshlrev_b32_e32 v8, 2, v8
	v_lshlrev_b32_e32 v9, 2, v9
	v_lshlrev_b32_e32 v3, 4, v2
	v_lshlrev_b32_e32 v2, 3, v2
	v_readlane_b32 s8, v252, 3
	v_readlane_b32 s9, v252, 4
	v_readlane_b32 s74, v252, 23
	v_readlane_b32 s75, v252, 24
	v_readlane_b32 s4, v252, 0
	s_nop 3
	s_add_u32 s36, s8, 0x2d39b600
	s_addc_u32 s37, s9, 0
	s_add_u32 s40, s8, 0x3239b600
	s_addc_u32 s41, s9, 0
	s_add_u32 s38, s8, 0x1899b600
	s_addc_u32 s39, s9, 0
	s_add_u32 s20, s8, 0x219be00
	s_addc_u32 s21, s9, 0
	s_lshl_b32 s4, s4, 3
	s_add_i32 s10, s4, s98
	s_mov_b32 s11, s99
.Lp6_main:
	s_mul_i32 s5, s11, 7
	s_add_i32 s5, s5, s10
	s_cmp_lt_u32 s5, 0x28000
	s_cbranch_scc0 .Lp6_tail
	s_mov_b32 s5, s10
	s_lshl_b32 s42, s5, 9
	s_lshr_b32 s43, s5, 2
	s_lshl_b32 s43, s43, 12
	s_and_b32 s64, s5, 3
	s_lshl_b32 s65, s64, 9
	s_add_i32 s43, s43, s65
	s_lshl_b32 s64, s64, 10
	v_add_u32_e32 v26, s42, v2
	v_add_u32_e32 v27, s43, v2
	v_add_u32_e32 v28, s64, v3
	s_add_i32 s5, s5, s11
	s_lshl_b32 s42, s5, 9
	s_lshr_b32 s43, s5, 2
	s_lshl_b32 s43, s43, 12
	s_and_b32 s64, s5, 3
	s_lshl_b32 s65, s64, 9
	s_add_i32 s43, s43, s65
	s_lshl_b32 s64, s64, 10
	v_add_u32_e32 v50, s42, v2
	v_add_u32_e32 v51, s43, v2
	v_add_u32_e32 v52, s64, v3
	s_add_i32 s5, s5, s11
	s_lshl_b32 s42, s5, 9
	s_lshr_b32 s43, s5, 2
	s_lshl_b32 s43, s43, 12
	s_and_b32 s64, s5, 3
	s_lshl_b32 s65, s64, 9
	s_add_i32 s43, s43, s65
	s_lshl_b32 s64, s64, 10
	v_add_u32_e32 v74, s42, v2
	v_add_u32_e32 v75, s43, v2
	v_add_u32_e32 v76, s64, v3
	s_add_i32 s5, s5, s11
	s_lshl_b32 s42, s5, 9
	s_lshr_b32 s43, s5, 2
	s_lshl_b32 s43, s43, 12
	s_and_b32 s64, s5, 3
	s_lshl_b32 s65, s64, 9
	s_add_i32 s43, s43, s65
	s_lshl_b32 s64, s64, 10
	v_add_u32_e32 v98, s42, v2
	v_add_u32_e32 v99, s43, v2
	v_add_u32_e32 v100, s64, v3
	s_add_i32 s5, s5, s11
	s_lshl_b32 s42, s5, 9
	s_lshr_b32 s43, s5, 2
	s_lshl_b32 s43, s43, 12
	s_and_b32 s64, s5, 3
	s_lshl_b32 s65, s64, 9
	s_add_i32 s43, s43, s65
	s_lshl_b32 s64, s64, 10
	v_add_u32_e32 v122, s42, v2
	v_add_u32_e32 v123, s43, v2
	v_add_u32_e32 v124, s64, v3
	s_add_i32 s5, s5, s11
	s_lshl_b32 s42, s5, 9
	s_lshr_b32 s43, s5, 2
	s_lshl_b32 s43, s43, 12
	s_and_b32 s64, s5, 3
	s_lshl_b32 s65, s64, 9
	s_add_i32 s43, s43, s65
	s_lshl_b32 s64, s64, 10
	v_add_u32_e32 v146, s42, v2
	v_add_u32_e32 v147, s43, v2
	v_add_u32_e32 v148, s64, v3
	s_add_i32 s5, s5, s11
	s_lshl_b32 s42, s5, 9
	s_lshr_b32 s43, s5, 2
	s_lshl_b32 s43, s43, 12
	s_and_b32 s64, s5, 3
	s_lshl_b32 s65, s64, 9
	s_add_i32 s43, s43, s65
	s_lshl_b32 s64, s64, 10
	v_add_u32_e32 v170, s42, v2
	v_add_u32_e32 v171, s43, v2
	v_add_u32_e32 v172, s64, v3
	s_add_i32 s5, s5, s11
	s_lshl_b32 s42, s5, 9
	s_lshr_b32 s43, s5, 2
	s_lshl_b32 s43, s43, 12
	s_and_b32 s64, s5, 3
	s_lshl_b32 s65, s64, 9
	s_add_i32 s43, s43, s65
	s_lshl_b32 s64, s64, 10
	v_add_u32_e32 v194, s42, v2
	v_add_u32_e32 v195, s43, v2
	v_add_u32_e32 v196, s64, v3
	global_load_dwordx2 v[16:17], v26, s[36:37]
	global_load_dwordx2 v[18:19], v26, s[40:41]
	global_load_dwordx2 v[40:41], v50, s[36:37]
	global_load_dwordx2 v[42:43], v50, s[40:41]
	global_load_dwordx2 v[64:65], v74, s[36:37]
	global_load_dwordx2 v[66:67], v74, s[40:41]
	global_load_dwordx2 v[88:89], v98, s[36:37]
	global_load_dwordx2 v[90:91], v98, s[40:41]
	global_load_dwordx2 v[112:113], v122, s[36:37]
	global_load_dwordx2 v[114:115], v122, s[40:41]
	global_load_dwordx2 v[136:137], v146, s[36:37]
	global_load_dwordx2 v[138:139], v146, s[40:41]
	global_load_dwordx2 v[160:161], v170, s[36:37]
	global_load_dwordx2 v[162:163], v170, s[40:41]
	global_load_dwordx2 v[184:185], v194, s[36:37]
	global_load_dwordx2 v[186:187], v194, s[40:41]
	global_load_dwordx2 v[20:21], v27, s[20:21]
	global_load_dwordx4 v[22:25], v28, s[74:75]
	global_load_dwordx2 v[44:45], v51, s[20:21]
	global_load_dwordx4 v[46:49], v52, s[74:75]
	global_load_dwordx2 v[68:69], v75, s[20:21]
	global_load_dwordx4 v[70:73], v76, s[74:75]
	global_load_dwordx2 v[92:93], v99, s[20:21]
	global_load_dwordx4 v[94:97], v100, s[74:75]
	global_load_dwordx2 v[116:117], v123, s[20:21]
	global_load_dwordx4 v[118:121], v124, s[74:75]
	global_load_dwordx2 v[140:141], v147, s[20:21]
	global_load_dwordx4 v[142:145], v148, s[74:75]
	global_load_dwordx2 v[164:165], v171, s[20:21]
	global_load_dwordx4 v[166:169], v172, s[74:75]
	global_load_dwordx2 v[188:189], v195, s[20:21]
	global_load_dwordx4 v[190:193], v196, s[74:75]
	s_waitcnt vmcnt(30)
	v_lshlrev_b32_e32 v30, 16, v16
	v_and_b32_e32 v31, 0xffff0000, v16
	v_lshlrev_b32_e32 v34, 16, v18
	v_and_b32_e32 v35, 0xffff0000, v18
	v_lshlrev_b32_e32 v32, 16, v17
	v_and_b32_e32 v33, 0xffff0000, v17
	v_lshlrev_b32_e32 v36, 16, v19
	v_and_b32_e32 v37, 0xffff0000, v19
	v_pk_add_f32 v[32:33], v[32:33], v[36:37]
	v_pk_add_f32 v[30:31], v[30:31], v[34:35]
	v_pk_mul_f32 v[36:37], v[32:33], v[32:33]
	v_pk_mul_f32 v[34:35], v[30:31], v[30:31]
	v_add_f32_e32 v29, v34, v35
	v_add_f32_e32 v29, v29, v36
	v_add_f32_e32 v29, v37, v29
	s_waitcnt vmcnt(28)
	v_lshlrev_b32_e32 v54, 16, v40
	v_and_b32_e32 v55, 0xffff0000, v40
	v_lshlrev_b32_e32 v58, 16, v42
	v_and_b32_e32 v59, 0xffff0000, v42
	v_lshlrev_b32_e32 v56, 16, v41
	v_and_b32_e32 v57, 0xffff0000, v41
	v_lshlrev_b32_e32 v60, 16, v43
	v_and_b32_e32 v61, 0xffff0000, v43
	v_pk_add_f32 v[56:57], v[56:57], v[60:61]
	v_pk_add_f32 v[54:55], v[54:55], v[58:59]
	v_pk_mul_f32 v[60:61], v[56:57], v[56:57]
	v_pk_mul_f32 v[58:59], v[54:55], v[54:55]
	v_add_f32_e32 v53, v58, v59
	v_add_f32_e32 v53, v53, v60
	v_add_f32_e32 v53, v61, v53
	s_waitcnt vmcnt(26)
	v_lshlrev_b32_e32 v78, 16, v64
	v_and_b32_e32 v79, 0xffff0000, v64
	v_lshlrev_b32_e32 v82, 16, v66
	v_and_b32_e32 v83, 0xffff0000, v66
	v_lshlrev_b32_e32 v80, 16, v65
	v_and_b32_e32 v81, 0xffff0000, v65
	v_lshlrev_b32_e32 v84, 16, v67
	v_and_b32_e32 v85, 0xffff0000, v67
	v_pk_add_f32 v[80:81], v[80:81], v[84:85]
	v_pk_add_f32 v[78:79], v[78:79], v[82:83]
	v_pk_mul_f32 v[84:85], v[80:81], v[80:81]
	v_pk_mul_f32 v[82:83], v[78:79], v[78:79]
	v_add_f32_e32 v77, v82, v83
	v_add_f32_e32 v77, v77, v84
	v_add_f32_e32 v77, v85, v77
	s_waitcnt vmcnt(24)
	v_lshlrev_b32_e32 v102, 16, v88
	v_and_b32_e32 v103, 0xffff0000, v88
	v_lshlrev_b32_e32 v106, 16, v90
	v_and_b32_e32 v107, 0xffff0000, v90
	v_lshlrev_b32_e32 v104, 16, v89
	v_and_b32_e32 v105, 0xffff0000, v89
	v_lshlrev_b32_e32 v108, 16, v91
	v_and_b32_e32 v109, 0xffff0000, v91
	v_pk_add_f32 v[104:105], v[104:105], v[108:109]
	v_pk_add_f32 v[102:103], v[102:103], v[106:107]
	v_pk_mul_f32 v[108:109], v[104:105], v[104:105]
	v_pk_mul_f32 v[106:107], v[102:103], v[102:103]
	v_add_f32_e32 v101, v106, v107
	v_add_f32_e32 v101, v101, v108
	v_add_f32_e32 v101, v109, v101
	s_waitcnt vmcnt(22)
	v_lshlrev_b32_e32 v126, 16, v112
	v_and_b32_e32 v127, 0xffff0000, v112
	v_lshlrev_b32_e32 v130, 16, v114
	v_and_b32_e32 v131, 0xffff0000, v114
	v_lshlrev_b32_e32 v128, 16, v113
	v_and_b32_e32 v129, 0xffff0000, v113
	v_lshlrev_b32_e32 v132, 16, v115
	v_and_b32_e32 v133, 0xffff0000, v115
	v_pk_add_f32 v[128:129], v[128:129], v[132:133]
	v_pk_add_f32 v[126:127], v[126:127], v[130:131]
	v_pk_mul_f32 v[132:133], v[128:129], v[128:129]
	v_pk_mul_f32 v[130:131], v[126:127], v[126:127]
	v_add_f32_e32 v125, v130, v131
	v_add_f32_e32 v125, v125, v132
	v_add_f32_e32 v125, v133, v125
	s_waitcnt vmcnt(20)
	v_lshlrev_b32_e32 v150, 16, v136
	v_and_b32_e32 v151, 0xffff0000, v136
	v_lshlrev_b32_e32 v154, 16, v138
	v_and_b32_e32 v155, 0xffff0000, v138
	v_lshlrev_b32_e32 v152, 16, v137
	v_and_b32_e32 v153, 0xffff0000, v137
	v_lshlrev_b32_e32 v156, 16, v139
	v_and_b32_e32 v157, 0xffff0000, v139
	v_pk_add_f32 v[152:153], v[152:153], v[156:157]
	v_pk_add_f32 v[150:151], v[150:151], v[154:155]
	v_pk_mul_f32 v[156:157], v[152:153], v[152:153]
	v_pk_mul_f32 v[154:155], v[150:151], v[150:151]
	v_add_f32_e32 v149, v154, v155
	v_add_f32_e32 v149, v149, v156
	v_add_f32_e32 v149, v157, v149
	s_waitcnt vmcnt(18)
	v_lshlrev_b32_e32 v174, 16, v160
	v_and_b32_e32 v175, 0xffff0000, v160
	v_lshlrev_b32_e32 v178, 16, v162
	v_and_b32_e32 v179, 0xffff0000, v162
	v_lshlrev_b32_e32 v176, 16, v161
	v_and_b32_e32 v177, 0xffff0000, v161
	v_lshlrev_b32_e32 v180, 16, v163
	v_and_b32_e32 v181, 0xffff0000, v163
	v_pk_add_f32 v[176:177], v[176:177], v[180:181]
	v_pk_add_f32 v[174:175], v[174:175], v[178:179]
	v_pk_mul_f32 v[180:181], v[176:177], v[176:177]
	v_pk_mul_f32 v[178:179], v[174:175], v[174:175]
	v_add_f32_e32 v173, v178, v179
	v_add_f32_e32 v173, v173, v180
	v_add_f32_e32 v173, v181, v173
	s_waitcnt vmcnt(16)
	v_lshlrev_b32_e32 v198, 16, v184
	v_and_b32_e32 v199, 0xffff0000, v184
	v_lshlrev_b32_e32 v202, 16, v186
	v_and_b32_e32 v203, 0xffff0000, v186
	v_lshlrev_b32_e32 v200, 16, v185
	v_and_b32_e32 v201, 0xffff0000, v185
	v_lshlrev_b32_e32 v204, 16, v187
	v_and_b32_e32 v205, 0xffff0000, v187
	v_pk_add_f32 v[200:201], v[200:201], v[204:205]
	v_pk_add_f32 v[198:199], v[198:199], v[202:203]
	v_pk_mul_f32 v[204:205], v[200:201], v[200:201]
	v_pk_mul_f32 v[202:203], v[198:199], v[198:199]
	v_add_f32_e32 v197, v202, v203
	v_add_f32_e32 v197, v197, v204
	v_add_f32_e32 v197, v205, v197
	ds_bpermute_b32 v34, v4, v29
	ds_bpermute_b32 v58, v4, v53
	ds_bpermute_b32 v82, v4, v77
	ds_bpermute_b32 v106, v4, v101
	ds_bpermute_b32 v130, v4, v125
	ds_bpermute_b32 v154, v4, v149
	ds_bpermute_b32 v178, v4, v173
	ds_bpermute_b32 v202, v4, v197
	s_waitcnt lgkmcnt(7)
	v_add_f32_e32 v29, v29, v34
	s_waitcnt lgkmcnt(6)
	v_add_f32_e32 v53, v53, v58
	s_waitcnt lgkmcnt(5)
	v_add_f32_e32 v77, v77, v82
	s_waitcnt lgkmcnt(4)
	v_add_f32_e32 v101, v101, v106
	s_waitcnt lgkmcnt(3)
	v_add_f32_e32 v125, v125, v130
	s_waitcnt lgkmcnt(2)
	v_add_f32_e32 v149, v149, v154
	s_waitcnt lgkmcnt(1)
	v_add_f32_e32 v173, v173, v178
	s_waitcnt lgkmcnt(0)
	v_add_f32_e32 v197, v197, v202
	ds_bpermute_b32 v34, v5, v29
	ds_bpermute_b32 v58, v5, v53
	ds_bpermute_b32 v82, v5, v77
	ds_bpermute_b32 v106, v5, v101
	ds_bpermute_b32 v130, v5, v125
	ds_bpermute_b32 v154, v5, v149
	ds_bpermute_b32 v178, v5, v173
	ds_bpermute_b32 v202, v5, v197
	s_waitcnt lgkmcnt(7)
	v_add_f32_e32 v29, v29, v34
	s_waitcnt lgkmcnt(6)
	v_add_f32_e32 v53, v53, v58
	s_waitcnt lgkmcnt(5)
	v_add_f32_e32 v77, v77, v82
	s_waitcnt lgkmcnt(4)
	v_add_f32_e32 v101, v101, v106
	s_waitcnt lgkmcnt(3)
	v_add_f32_e32 v125, v125, v130
	s_waitcnt lgkmcnt(2)
	v_add_f32_e32 v149, v149, v154
	s_waitcnt lgkmcnt(1)
	v_add_f32_e32 v173, v173, v178
	s_waitcnt lgkmcnt(0)
	v_add_f32_e32 v197, v197, v202
	ds_bpermute_b32 v34, v6, v29
	ds_bpermute_b32 v58, v6, v53
	ds_bpermute_b32 v82, v6, v77
	ds_bpermute_b32 v106, v6, v101
	ds_bpermute_b32 v130, v6, v125
	ds_bpermute_b32 v154, v6, v149
	ds_bpermute_b32 v178, v6, v173
	ds_bpermute_b32 v202, v6, v197
	s_waitcnt lgkmcnt(7)
	v_add_f32_e32 v29, v29, v34
	s_waitcnt lgkmcnt(6)
	v_add_f32_e32 v53, v53, v58
	s_waitcnt lgkmcnt(5)
	v_add_f32_e32 v77, v77, v82
	s_waitcnt lgkmcnt(4)
	v_add_f32_e32 v101, v101, v106
	s_waitcnt lgkmcnt(3)
	v_add_f32_e32 v125, v125, v130
	s_waitcnt lgkmcnt(2)
	v_add_f32_e32 v149, v149, v154
	s_waitcnt lgkmcnt(1)
	v_add_f32_e32 v173, v173, v178
	s_waitcnt lgkmcnt(0)
	v_add_f32_e32 v197, v197, v202
	ds_bpermute_b32 v34, v7, v29
	ds_bpermute_b32 v58, v7, v53
	ds_bpermute_b32 v82, v7, v77
	ds_bpermute_b32 v106, v7, v101
	ds_bpermute_b32 v130, v7, v125
	ds_bpermute_b32 v154, v7, v149
	ds_bpermute_b32 v178, v7, v173
	ds_bpermute_b32 v202, v7, v197
	s_waitcnt lgkmcnt(7)
	v_add_f32_e32 v29, v29, v34
	s_waitcnt lgkmcnt(6)
	v_add_f32_e32 v53, v53, v58
	s_waitcnt lgkmcnt(5)
	v_add_f32_e32 v77, v77, v82
	s_waitcnt lgkmcnt(4)
	v_add_f32_e32 v101, v101, v106
	s_waitcnt lgkmcnt(3)
	v_add_f32_e32 v125, v125, v130
	s_waitcnt lgkmcnt(2)
	v_add_f32_e32 v149, v149, v154
	s_waitcnt lgkmcnt(1)
	v_add_f32_e32 v173, v173, v178
	s_waitcnt lgkmcnt(0)
	v_add_f32_e32 v197, v197, v202
	ds_bpermute_b32 v34, v8, v29
	ds_bpermute_b32 v58, v8, v53
	ds_bpermute_b32 v82, v8, v77
	ds_bpermute_b32 v106, v8, v101
	ds_bpermute_b32 v130, v8, v125
	ds_bpermute_b32 v154, v8, v149
	ds_bpermute_b32 v178, v8, v173
	ds_bpermute_b32 v202, v8, v197
	s_waitcnt lgkmcnt(7)
	v_add_f32_e32 v29, v29, v34
	s_waitcnt lgkmcnt(6)
	v_add_f32_e32 v53, v53, v58
	s_waitcnt lgkmcnt(5)
	v_add_f32_e32 v77, v77, v82
	s_waitcnt lgkmcnt(4)
	v_add_f32_e32 v101, v101, v106
	s_waitcnt lgkmcnt(3)
	v_add_f32_e32 v125, v125, v130
	s_waitcnt lgkmcnt(2)
	v_add_f32_e32 v149, v149, v154
	s_waitcnt lgkmcnt(1)
	v_add_f32_e32 v173, v173, v178
	s_waitcnt lgkmcnt(0)
	v_add_f32_e32 v197, v197, v202
	ds_bpermute_b32 v34, v9, v29
	ds_bpermute_b32 v58, v9, v53
	ds_bpermute_b32 v82, v9, v77
	ds_bpermute_b32 v106, v9, v101
	ds_bpermute_b32 v130, v9, v125
	ds_bpermute_b32 v154, v9, v149
	ds_bpermute_b32 v178, v9, v173
	ds_bpermute_b32 v202, v9, v197
	s_waitcnt lgkmcnt(7)
	v_add_f32_e32 v29, v29, v34
	s_waitcnt lgkmcnt(6)
	v_add_f32_e32 v53, v53, v58
	s_waitcnt lgkmcnt(5)
	v_add_f32_e32 v77, v77, v82
	s_waitcnt lgkmcnt(4)
	v_add_f32_e32 v101, v101, v106
	s_waitcnt lgkmcnt(3)
	v_add_f32_e32 v125, v125, v130
	s_waitcnt lgkmcnt(2)
	v_add_f32_e32 v149, v149, v154
	s_waitcnt lgkmcnt(1)
	v_add_f32_e32 v173, v173, v178
	s_waitcnt lgkmcnt(0)
	v_add_f32_e32 v197, v197, v202
	s_waitcnt vmcnt(0)
	v_fmamk_f32 v0, v29, 0x3b800000, v230
	v_rsq_f32_e32 v0, v0
	v_lshlrev_b32_e32 v34, 16, v20
	v_and_b32_e32 v35, 0xffff0000, v20
	v_lshlrev_b32_e32 v36, 16, v21
	v_and_b32_e32 v37, 0xffff0000, v21
	v_pk_mul_f32 v[30:31], v[30:31], v[0:1] op_sel_hi:[1,0]
	v_pk_mul_f32 v[32:33], v[32:33], v[0:1] op_sel_hi:[1,0]
	v_pk_mul_f32 v[30:31], v[22:23], v[30:31]
	v_pk_mul_f32 v[32:33], v[24:25], v[32:33]
	v_mul_f32_e32 v16, 0xbfb8aa3b, v34
	v_exp_f32_e32 v16, v16
	s_nop 0
	v_add_f32_e32 v16, 1.0, v16
	v_div_scale_f32 v17, s[4:5], v16, v16, v34
	v_rcp_f32_e32 v18, v17
	s_nop 0
	v_fma_f32 v19, -v17, v18, 1.0
	v_fmac_f32_e32 v18, v19, v18
	v_div_scale_f32 v19, vcc, v34, v16, v34
	v_mul_f32_e32 v38, v19, v18
	v_fma_f32 v39, -v17, v38, v19
	v_fmac_f32_e32 v38, v39, v18
	v_fma_f32 v17, -v17, v38, v19
	v_div_fmas_f32 v17, v17, v18, v38
	v_div_fixup_f32 v34, v17, v16, v34
	v_mul_f32_e32 v16, 0xbfb8aa3b, v35
	v_exp_f32_e32 v16, v16
	s_nop 0
	v_add_f32_e32 v16, 1.0, v16
	v_div_scale_f32 v17, s[4:5], v16, v16, v35
	v_rcp_f32_e32 v18, v17
	s_nop 0
	v_fma_f32 v19, -v17, v18, 1.0
	v_fmac_f32_e32 v18, v19, v18
	v_div_scale_f32 v19, vcc, v35, v16, v35
	v_mul_f32_e32 v38, v19, v18
	v_fma_f32 v39, -v17, v38, v19
	v_fmac_f32_e32 v38, v39, v18
	v_fma_f32 v17, -v17, v38, v19
	v_div_fmas_f32 v17, v17, v18, v38
	v_div_fixup_f32 v35, v17, v16, v35
	v_mul_f32_e32 v16, 0xbfb8aa3b, v36
	v_exp_f32_e32 v16, v16
	s_nop 0
	v_add_f32_e32 v16, 1.0, v16
	v_div_scale_f32 v17, s[4:5], v16, v16, v36
	v_rcp_f32_e32 v18, v17
	s_nop 0
	v_fma_f32 v19, -v17, v18, 1.0
	v_fmac_f32_e32 v18, v19, v18
	v_div_scale_f32 v19, vcc, v36, v16, v36
	v_mul_f32_e32 v38, v19, v18
	v_fma_f32 v39, -v17, v38, v19
	v_fmac_f32_e32 v38, v39, v18
	v_fma_f32 v17, -v17, v38, v19
	v_div_fmas_f32 v17, v17, v18, v38
	v_div_fixup_f32 v36, v17, v16, v36
	v_mul_f32_e32 v16, 0xbfb8aa3b, v37
	v_exp_f32_e32 v16, v16
	s_nop 0
	v_add_f32_e32 v16, 1.0, v16
	v_div_scale_f32 v17, s[4:5], v16, v16, v37
	v_rcp_f32_e32 v18, v17
	s_nop 0
	v_fma_f32 v19, -v17, v18, 1.0
	v_fmac_f32_e32 v18, v19, v18
	v_div_scale_f32 v19, vcc, v37, v16, v37
	v_mul_f32_e32 v38, v19, v18
	v_fma_f32 v39, -v17, v38, v19
	v_fmac_f32_e32 v38, v39, v18
	v_fma_f32 v17, -v17, v38, v19
	v_div_fmas_f32 v17, v17, v18, v38
	v_div_fixup_f32 v37, v17, v16, v37
	v_pk_mul_f32 v[30:31], v[34:35], v[30:31]
	v_pk_mul_f32 v[32:33], v[36:37], v[32:33]
	v_cvt_pk_bf16_f32 v30, v30, v31
	v_cvt_pk_bf16_f32 v31, v32, v33
	global_store_dwordx2 v26, v[30:31], s[38:39]
	v_fmamk_f32 v0, v53, 0x3b800000, v230
	v_rsq_f32_e32 v0, v0
	v_lshlrev_b32_e32 v58, 16, v44
	v_and_b32_e32 v59, 0xffff0000, v44
	v_lshlrev_b32_e32 v60, 16, v45
	v_and_b32_e32 v61, 0xffff0000, v45
	v_pk_mul_f32 v[54:55], v[54:55], v[0:1] op_sel_hi:[1,0]
	v_pk_mul_f32 v[56:57], v[56:57], v[0:1] op_sel_hi:[1,0]
	v_pk_mul_f32 v[54:55], v[46:47], v[54:55]
	v_pk_mul_f32 v[56:57], v[48:49], v[56:57]
	v_mul_f32_e32 v40, 0xbfb8aa3b, v58
	v_exp_f32_e32 v40, v40
	s_nop 0
	v_add_f32_e32 v40, 1.0, v40
	v_div_scale_f32 v41, s[4:5], v40, v40, v58
	v_rcp_f32_e32 v42, v41
	s_nop 0
	v_fma_f32 v43, -v41, v42, 1.0
	v_fmac_f32_e32 v42, v43, v42
	v_div_scale_f32 v43, vcc, v58, v40, v58
	v_mul_f32_e32 v62, v43, v42
	v_fma_f32 v63, -v41, v62, v43
	v_fmac_f32_e32 v62, v63, v42
	v_fma_f32 v41, -v41, v62, v43
	v_div_fmas_f32 v41, v41, v42, v62
	v_div_fixup_f32 v58, v41, v40, v58
	v_mul_f32_e32 v40, 0xbfb8aa3b, v59
	v_exp_f32_e32 v40, v40
	s_nop 0
	v_add_f32_e32 v40, 1.0, v40
	v_div_scale_f32 v41, s[4:5], v40, v40, v59
	v_rcp_f32_e32 v42, v41
	s_nop 0
	v_fma_f32 v43, -v41, v42, 1.0
	v_fmac_f32_e32 v42, v43, v42
	v_div_scale_f32 v43, vcc, v59, v40, v59
	v_mul_f32_e32 v62, v43, v42
	v_fma_f32 v63, -v41, v62, v43
	v_fmac_f32_e32 v62, v63, v42
	v_fma_f32 v41, -v41, v62, v43
	v_div_fmas_f32 v41, v41, v42, v62
	v_div_fixup_f32 v59, v41, v40, v59
	v_mul_f32_e32 v40, 0xbfb8aa3b, v60
	v_exp_f32_e32 v40, v40
	s_nop 0
	v_add_f32_e32 v40, 1.0, v40
	v_div_scale_f32 v41, s[4:5], v40, v40, v60
	v_rcp_f32_e32 v42, v41
	s_nop 0
	v_fma_f32 v43, -v41, v42, 1.0
	v_fmac_f32_e32 v42, v43, v42
	v_div_scale_f32 v43, vcc, v60, v40, v60
	v_mul_f32_e32 v62, v43, v42
	v_fma_f32 v63, -v41, v62, v43
	v_fmac_f32_e32 v62, v63, v42
	v_fma_f32 v41, -v41, v62, v43
	v_div_fmas_f32 v41, v41, v42, v62
	v_div_fixup_f32 v60, v41, v40, v60
	v_mul_f32_e32 v40, 0xbfb8aa3b, v61
	v_exp_f32_e32 v40, v40
	s_nop 0
	v_add_f32_e32 v40, 1.0, v40
	v_div_scale_f32 v41, s[4:5], v40, v40, v61
	v_rcp_f32_e32 v42, v41
	s_nop 0
	v_fma_f32 v43, -v41, v42, 1.0
	v_fmac_f32_e32 v42, v43, v42
	v_div_scale_f32 v43, vcc, v61, v40, v61
	v_mul_f32_e32 v62, v43, v42
	v_fma_f32 v63, -v41, v62, v43
	v_fmac_f32_e32 v62, v63, v42
	v_fma_f32 v41, -v41, v62, v43
	v_div_fmas_f32 v41, v41, v42, v62
	v_div_fixup_f32 v61, v41, v40, v61
	v_pk_mul_f32 v[54:55], v[58:59], v[54:55]
	v_pk_mul_f32 v[56:57], v[60:61], v[56:57]
	v_cvt_pk_bf16_f32 v54, v54, v55
	v_cvt_pk_bf16_f32 v55, v56, v57
	global_store_dwordx2 v50, v[54:55], s[38:39]
	v_fmamk_f32 v0, v77, 0x3b800000, v230
	v_rsq_f32_e32 v0, v0
	v_lshlrev_b32_e32 v82, 16, v68
	v_and_b32_e32 v83, 0xffff0000, v68
	v_lshlrev_b32_e32 v84, 16, v69
	v_and_b32_e32 v85, 0xffff0000, v69
	v_pk_mul_f32 v[78:79], v[78:79], v[0:1] op_sel_hi:[1,0]
	v_pk_mul_f32 v[80:81], v[80:81], v[0:1] op_sel_hi:[1,0]
	v_pk_mul_f32 v[78:79], v[70:71], v[78:79]
	v_pk_mul_f32 v[80:81], v[72:73], v[80:81]
	v_mul_f32_e32 v64, 0xbfb8aa3b, v82
	v_exp_f32_e32 v64, v64
	s_nop 0
	v_add_f32_e32 v64, 1.0, v64
	v_div_scale_f32 v65, s[4:5], v64, v64, v82
	v_rcp_f32_e32 v66, v65
	s_nop 0
	v_fma_f32 v67, -v65, v66, 1.0
	v_fmac_f32_e32 v66, v67, v66
	v_div_scale_f32 v67, vcc, v82, v64, v82
	v_mul_f32_e32 v86, v67, v66
	v_fma_f32 v87, -v65, v86, v67
	v_fmac_f32_e32 v86, v87, v66
	v_fma_f32 v65, -v65, v86, v67
	v_div_fmas_f32 v65, v65, v66, v86
	v_div_fixup_f32 v82, v65, v64, v82
	v_mul_f32_e32 v64, 0xbfb8aa3b, v83
	v_exp_f32_e32 v64, v64
	s_nop 0
	v_add_f32_e32 v64, 1.0, v64
	v_div_scale_f32 v65, s[4:5], v64, v64, v83
	v_rcp_f32_e32 v66, v65
	s_nop 0
	v_fma_f32 v67, -v65, v66, 1.0
	v_fmac_f32_e32 v66, v67, v66
	v_div_scale_f32 v67, vcc, v83, v64, v83
	v_mul_f32_e32 v86, v67, v66
	v_fma_f32 v87, -v65, v86, v67
	v_fmac_f32_e32 v86, v87, v66
	v_fma_f32 v65, -v65, v86, v67
	v_div_fmas_f32 v65, v65, v66, v86
	v_div_fixup_f32 v83, v65, v64, v83
	v_mul_f32_e32 v64, 0xbfb8aa3b, v84
	v_exp_f32_e32 v64, v64
	s_nop 0
	v_add_f32_e32 v64, 1.0, v64
	v_div_scale_f32 v65, s[4:5], v64, v64, v84
	v_rcp_f32_e32 v66, v65
	s_nop 0
	v_fma_f32 v67, -v65, v66, 1.0
	v_fmac_f32_e32 v66, v67, v66
	v_div_scale_f32 v67, vcc, v84, v64, v84
	v_mul_f32_e32 v86, v67, v66
	v_fma_f32 v87, -v65, v86, v67
	v_fmac_f32_e32 v86, v87, v66
	v_fma_f32 v65, -v65, v86, v67
	v_div_fmas_f32 v65, v65, v66, v86
	v_div_fixup_f32 v84, v65, v64, v84
	v_mul_f32_e32 v64, 0xbfb8aa3b, v85
	v_exp_f32_e32 v64, v64
	s_nop 0
	v_add_f32_e32 v64, 1.0, v64
	v_div_scale_f32 v65, s[4:5], v64, v64, v85
	v_rcp_f32_e32 v66, v65
	s_nop 0
	v_fma_f32 v67, -v65, v66, 1.0
	v_fmac_f32_e32 v66, v67, v66
	v_div_scale_f32 v67, vcc, v85, v64, v85
	v_mul_f32_e32 v86, v67, v66
	v_fma_f32 v87, -v65, v86, v67
	v_fmac_f32_e32 v86, v87, v66
	v_fma_f32 v65, -v65, v86, v67
	v_div_fmas_f32 v65, v65, v66, v86
	v_div_fixup_f32 v85, v65, v64, v85
	v_pk_mul_f32 v[78:79], v[82:83], v[78:79]
	v_pk_mul_f32 v[80:81], v[84:85], v[80:81]
	v_cvt_pk_bf16_f32 v78, v78, v79
	v_cvt_pk_bf16_f32 v79, v80, v81
	global_store_dwordx2 v74, v[78:79], s[38:39]
	v_fmamk_f32 v0, v101, 0x3b800000, v230
	v_rsq_f32_e32 v0, v0
	v_lshlrev_b32_e32 v106, 16, v92
	v_and_b32_e32 v107, 0xffff0000, v92
	v_lshlrev_b32_e32 v108, 16, v93
	v_and_b32_e32 v109, 0xffff0000, v93
	v_pk_mul_f32 v[102:103], v[102:103], v[0:1] op_sel_hi:[1,0]
	v_pk_mul_f32 v[104:105], v[104:105], v[0:1] op_sel_hi:[1,0]
	v_pk_mul_f32 v[102:103], v[94:95], v[102:103]
	v_pk_mul_f32 v[104:105], v[96:97], v[104:105]
	v_mul_f32_e32 v88, 0xbfb8aa3b, v106
	v_exp_f32_e32 v88, v88
	s_nop 0
	v_add_f32_e32 v88, 1.0, v88
	v_div_scale_f32 v89, s[4:5], v88, v88, v106
	v_rcp_f32_e32 v90, v89
	s_nop 0
	v_fma_f32 v91, -v89, v90, 1.0
	v_fmac_f32_e32 v90, v91, v90
	v_div_scale_f32 v91, vcc, v106, v88, v106
	v_mul_f32_e32 v110, v91, v90
	v_fma_f32 v111, -v89, v110, v91
	v_fmac_f32_e32 v110, v111, v90
	v_fma_f32 v89, -v89, v110, v91
	v_div_fmas_f32 v89, v89, v90, v110
	v_div_fixup_f32 v106, v89, v88, v106
	v_mul_f32_e32 v88, 0xbfb8aa3b, v107
	v_exp_f32_e32 v88, v88
	s_nop 0
	v_add_f32_e32 v88, 1.0, v88
	v_div_scale_f32 v89, s[4:5], v88, v88, v107
	v_rcp_f32_e32 v90, v89
	s_nop 0
	v_fma_f32 v91, -v89, v90, 1.0
	v_fmac_f32_e32 v90, v91, v90
	v_div_scale_f32 v91, vcc, v107, v88, v107
	v_mul_f32_e32 v110, v91, v90
	v_fma_f32 v111, -v89, v110, v91
	v_fmac_f32_e32 v110, v111, v90
	v_fma_f32 v89, -v89, v110, v91
	v_div_fmas_f32 v89, v89, v90, v110
	v_div_fixup_f32 v107, v89, v88, v107
	v_mul_f32_e32 v88, 0xbfb8aa3b, v108
	v_exp_f32_e32 v88, v88
	s_nop 0
	v_add_f32_e32 v88, 1.0, v88
	v_div_scale_f32 v89, s[4:5], v88, v88, v108
	v_rcp_f32_e32 v90, v89
	s_nop 0
	v_fma_f32 v91, -v89, v90, 1.0
	v_fmac_f32_e32 v90, v91, v90
	v_div_scale_f32 v91, vcc, v108, v88, v108
	v_mul_f32_e32 v110, v91, v90
	v_fma_f32 v111, -v89, v110, v91
	v_fmac_f32_e32 v110, v111, v90
	v_fma_f32 v89, -v89, v110, v91
	v_div_fmas_f32 v89, v89, v90, v110
	v_div_fixup_f32 v108, v89, v88, v108
	v_mul_f32_e32 v88, 0xbfb8aa3b, v109
	v_exp_f32_e32 v88, v88
	s_nop 0
	v_add_f32_e32 v88, 1.0, v88
	v_div_scale_f32 v89, s[4:5], v88, v88, v109
	v_rcp_f32_e32 v90, v89
	s_nop 0
	v_fma_f32 v91, -v89, v90, 1.0
	v_fmac_f32_e32 v90, v91, v90
	v_div_scale_f32 v91, vcc, v109, v88, v109
	v_mul_f32_e32 v110, v91, v90
	v_fma_f32 v111, -v89, v110, v91
	v_fmac_f32_e32 v110, v111, v90
	v_fma_f32 v89, -v89, v110, v91
	v_div_fmas_f32 v89, v89, v90, v110
	v_div_fixup_f32 v109, v89, v88, v109
	v_pk_mul_f32 v[102:103], v[106:107], v[102:103]
	v_pk_mul_f32 v[104:105], v[108:109], v[104:105]
	v_cvt_pk_bf16_f32 v102, v102, v103
	v_cvt_pk_bf16_f32 v103, v104, v105
	global_store_dwordx2 v98, v[102:103], s[38:39]
	v_fmamk_f32 v0, v125, 0x3b800000, v230
	v_rsq_f32_e32 v0, v0
	v_lshlrev_b32_e32 v130, 16, v116
	v_and_b32_e32 v131, 0xffff0000, v116
	v_lshlrev_b32_e32 v132, 16, v117
	v_and_b32_e32 v133, 0xffff0000, v117
	v_pk_mul_f32 v[126:127], v[126:127], v[0:1] op_sel_hi:[1,0]
	v_pk_mul_f32 v[128:129], v[128:129], v[0:1] op_sel_hi:[1,0]
	v_pk_mul_f32 v[126:127], v[118:119], v[126:127]
	v_pk_mul_f32 v[128:129], v[120:121], v[128:129]
	v_mul_f32_e32 v112, 0xbfb8aa3b, v130
	v_exp_f32_e32 v112, v112
	s_nop 0
	v_add_f32_e32 v112, 1.0, v112
	v_div_scale_f32 v113, s[4:5], v112, v112, v130
	v_rcp_f32_e32 v114, v113
	s_nop 0
	v_fma_f32 v115, -v113, v114, 1.0
	v_fmac_f32_e32 v114, v115, v114
	v_div_scale_f32 v115, vcc, v130, v112, v130
	v_mul_f32_e32 v134, v115, v114
	v_fma_f32 v135, -v113, v134, v115
	v_fmac_f32_e32 v134, v135, v114
	v_fma_f32 v113, -v113, v134, v115
	v_div_fmas_f32 v113, v113, v114, v134
	v_div_fixup_f32 v130, v113, v112, v130
	v_mul_f32_e32 v112, 0xbfb8aa3b, v131
	v_exp_f32_e32 v112, v112
	s_nop 0
	v_add_f32_e32 v112, 1.0, v112
	v_div_scale_f32 v113, s[4:5], v112, v112, v131
	v_rcp_f32_e32 v114, v113
	s_nop 0
	v_fma_f32 v115, -v113, v114, 1.0
	v_fmac_f32_e32 v114, v115, v114
	v_div_scale_f32 v115, vcc, v131, v112, v131
	v_mul_f32_e32 v134, v115, v114
	v_fma_f32 v135, -v113, v134, v115
	v_fmac_f32_e32 v134, v135, v114
	v_fma_f32 v113, -v113, v134, v115
	v_div_fmas_f32 v113, v113, v114, v134
	v_div_fixup_f32 v131, v113, v112, v131
	v_mul_f32_e32 v112, 0xbfb8aa3b, v132
	v_exp_f32_e32 v112, v112
	s_nop 0
	v_add_f32_e32 v112, 1.0, v112
	v_div_scale_f32 v113, s[4:5], v112, v112, v132
	v_rcp_f32_e32 v114, v113
	s_nop 0
	v_fma_f32 v115, -v113, v114, 1.0
	v_fmac_f32_e32 v114, v115, v114
	v_div_scale_f32 v115, vcc, v132, v112, v132
	v_mul_f32_e32 v134, v115, v114
	v_fma_f32 v135, -v113, v134, v115
	v_fmac_f32_e32 v134, v135, v114
	v_fma_f32 v113, -v113, v134, v115
	v_div_fmas_f32 v113, v113, v114, v134
	v_div_fixup_f32 v132, v113, v112, v132
	v_mul_f32_e32 v112, 0xbfb8aa3b, v133
	v_exp_f32_e32 v112, v112
	s_nop 0
	v_add_f32_e32 v112, 1.0, v112
	v_div_scale_f32 v113, s[4:5], v112, v112, v133
	v_rcp_f32_e32 v114, v113
	s_nop 0
	v_fma_f32 v115, -v113, v114, 1.0
	v_fmac_f32_e32 v114, v115, v114
	v_div_scale_f32 v115, vcc, v133, v112, v133
	v_mul_f32_e32 v134, v115, v114
	v_fma_f32 v135, -v113, v134, v115
	v_fmac_f32_e32 v134, v135, v114
	v_fma_f32 v113, -v113, v134, v115
	v_div_fmas_f32 v113, v113, v114, v134
	v_div_fixup_f32 v133, v113, v112, v133
	v_pk_mul_f32 v[126:127], v[130:131], v[126:127]
	v_pk_mul_f32 v[128:129], v[132:133], v[128:129]
	v_cvt_pk_bf16_f32 v126, v126, v127
	v_cvt_pk_bf16_f32 v127, v128, v129
	global_store_dwordx2 v122, v[126:127], s[38:39]
	v_fmamk_f32 v0, v149, 0x3b800000, v230
	v_rsq_f32_e32 v0, v0
	v_lshlrev_b32_e32 v154, 16, v140
	v_and_b32_e32 v155, 0xffff0000, v140
	v_lshlrev_b32_e32 v156, 16, v141
	v_and_b32_e32 v157, 0xffff0000, v141
	v_pk_mul_f32 v[150:151], v[150:151], v[0:1] op_sel_hi:[1,0]
	v_pk_mul_f32 v[152:153], v[152:153], v[0:1] op_sel_hi:[1,0]
	v_pk_mul_f32 v[150:151], v[142:143], v[150:151]
	v_pk_mul_f32 v[152:153], v[144:145], v[152:153]
	v_mul_f32_e32 v136, 0xbfb8aa3b, v154
	v_exp_f32_e32 v136, v136
	s_nop 0
	v_add_f32_e32 v136, 1.0, v136
	v_div_scale_f32 v137, s[4:5], v136, v136, v154
	v_rcp_f32_e32 v138, v137
	s_nop 0
	v_fma_f32 v139, -v137, v138, 1.0
	v_fmac_f32_e32 v138, v139, v138
	v_div_scale_f32 v139, vcc, v154, v136, v154
	v_mul_f32_e32 v158, v139, v138
	v_fma_f32 v159, -v137, v158, v139
	v_fmac_f32_e32 v158, v159, v138
	v_fma_f32 v137, -v137, v158, v139
	v_div_fmas_f32 v137, v137, v138, v158
	v_div_fixup_f32 v154, v137, v136, v154
	v_mul_f32_e32 v136, 0xbfb8aa3b, v155
	v_exp_f32_e32 v136, v136
	s_nop 0
	v_add_f32_e32 v136, 1.0, v136
	v_div_scale_f32 v137, s[4:5], v136, v136, v155
	v_rcp_f32_e32 v138, v137
	s_nop 0
	v_fma_f32 v139, -v137, v138, 1.0
	v_fmac_f32_e32 v138, v139, v138
	v_div_scale_f32 v139, vcc, v155, v136, v155
	v_mul_f32_e32 v158, v139, v138
	v_fma_f32 v159, -v137, v158, v139
	v_fmac_f32_e32 v158, v159, v138
	v_fma_f32 v137, -v137, v158, v139
	v_div_fmas_f32 v137, v137, v138, v158
	v_div_fixup_f32 v155, v137, v136, v155
	v_mul_f32_e32 v136, 0xbfb8aa3b, v156
	v_exp_f32_e32 v136, v136
	s_nop 0
	v_add_f32_e32 v136, 1.0, v136
	v_div_scale_f32 v137, s[4:5], v136, v136, v156
	v_rcp_f32_e32 v138, v137
	s_nop 0
	v_fma_f32 v139, -v137, v138, 1.0
	v_fmac_f32_e32 v138, v139, v138
	v_div_scale_f32 v139, vcc, v156, v136, v156
	v_mul_f32_e32 v158, v139, v138
	v_fma_f32 v159, -v137, v158, v139
	v_fmac_f32_e32 v158, v159, v138
	v_fma_f32 v137, -v137, v158, v139
	v_div_fmas_f32 v137, v137, v138, v158
	v_div_fixup_f32 v156, v137, v136, v156
	v_mul_f32_e32 v136, 0xbfb8aa3b, v157
	v_exp_f32_e32 v136, v136
	s_nop 0
	v_add_f32_e32 v136, 1.0, v136
	v_div_scale_f32 v137, s[4:5], v136, v136, v157
	v_rcp_f32_e32 v138, v137
	s_nop 0
	v_fma_f32 v139, -v137, v138, 1.0
	v_fmac_f32_e32 v138, v139, v138
	v_div_scale_f32 v139, vcc, v157, v136, v157
	v_mul_f32_e32 v158, v139, v138
	v_fma_f32 v159, -v137, v158, v139
	v_fmac_f32_e32 v158, v159, v138
	v_fma_f32 v137, -v137, v158, v139
	v_div_fmas_f32 v137, v137, v138, v158
	v_div_fixup_f32 v157, v137, v136, v157
	v_pk_mul_f32 v[150:151], v[154:155], v[150:151]
	v_pk_mul_f32 v[152:153], v[156:157], v[152:153]
	v_cvt_pk_bf16_f32 v150, v150, v151
	v_cvt_pk_bf16_f32 v151, v152, v153
	global_store_dwordx2 v146, v[150:151], s[38:39]
	v_fmamk_f32 v0, v173, 0x3b800000, v230
	v_rsq_f32_e32 v0, v0
	v_lshlrev_b32_e32 v178, 16, v164
	v_and_b32_e32 v179, 0xffff0000, v164
	v_lshlrev_b32_e32 v180, 16, v165
	v_and_b32_e32 v181, 0xffff0000, v165
	v_pk_mul_f32 v[174:175], v[174:175], v[0:1] op_sel_hi:[1,0]
	v_pk_mul_f32 v[176:177], v[176:177], v[0:1] op_sel_hi:[1,0]
	v_pk_mul_f32 v[174:175], v[166:167], v[174:175]
	v_pk_mul_f32 v[176:177], v[168:169], v[176:177]
	v_mul_f32_e32 v160, 0xbfb8aa3b, v178
	v_exp_f32_e32 v160, v160
	s_nop 0
	v_add_f32_e32 v160, 1.0, v160
	v_div_scale_f32 v161, s[4:5], v160, v160, v178
	v_rcp_f32_e32 v162, v161
	s_nop 0
	v_fma_f32 v163, -v161, v162, 1.0
	v_fmac_f32_e32 v162, v163, v162
	v_div_scale_f32 v163, vcc, v178, v160, v178
	v_mul_f32_e32 v182, v163, v162
	v_fma_f32 v183, -v161, v182, v163
	v_fmac_f32_e32 v182, v183, v162
	v_fma_f32 v161, -v161, v182, v163
	v_div_fmas_f32 v161, v161, v162, v182
	v_div_fixup_f32 v178, v161, v160, v178
	v_mul_f32_e32 v160, 0xbfb8aa3b, v179
	v_exp_f32_e32 v160, v160
	s_nop 0
	v_add_f32_e32 v160, 1.0, v160
	v_div_scale_f32 v161, s[4:5], v160, v160, v179
	v_rcp_f32_e32 v162, v161
	s_nop 0
	v_fma_f32 v163, -v161, v162, 1.0
	v_fmac_f32_e32 v162, v163, v162
	v_div_scale_f32 v163, vcc, v179, v160, v179
	v_mul_f32_e32 v182, v163, v162
	v_fma_f32 v183, -v161, v182, v163
	v_fmac_f32_e32 v182, v183, v162
	v_fma_f32 v161, -v161, v182, v163
	v_div_fmas_f32 v161, v161, v162, v182
	v_div_fixup_f32 v179, v161, v160, v179
	v_mul_f32_e32 v160, 0xbfb8aa3b, v180
	v_exp_f32_e32 v160, v160
	s_nop 0
	v_add_f32_e32 v160, 1.0, v160
	v_div_scale_f32 v161, s[4:5], v160, v160, v180
	v_rcp_f32_e32 v162, v161
	s_nop 0
	v_fma_f32 v163, -v161, v162, 1.0
	v_fmac_f32_e32 v162, v163, v162
	v_div_scale_f32 v163, vcc, v180, v160, v180
	v_mul_f32_e32 v182, v163, v162
	v_fma_f32 v183, -v161, v182, v163
	v_fmac_f32_e32 v182, v183, v162
	v_fma_f32 v161, -v161, v182, v163
	v_div_fmas_f32 v161, v161, v162, v182
	v_div_fixup_f32 v180, v161, v160, v180
	v_mul_f32_e32 v160, 0xbfb8aa3b, v181
	v_exp_f32_e32 v160, v160
	s_nop 0
	v_add_f32_e32 v160, 1.0, v160
	v_div_scale_f32 v161, s[4:5], v160, v160, v181
	v_rcp_f32_e32 v162, v161
	s_nop 0
	v_fma_f32 v163, -v161, v162, 1.0
	v_fmac_f32_e32 v162, v163, v162
	v_div_scale_f32 v163, vcc, v181, v160, v181
	v_mul_f32_e32 v182, v163, v162
	v_fma_f32 v183, -v161, v182, v163
	v_fmac_f32_e32 v182, v183, v162
	v_fma_f32 v161, -v161, v182, v163
	v_div_fmas_f32 v161, v161, v162, v182
	v_div_fixup_f32 v181, v161, v160, v181
	v_pk_mul_f32 v[174:175], v[178:179], v[174:175]
	v_pk_mul_f32 v[176:177], v[180:181], v[176:177]
	v_cvt_pk_bf16_f32 v174, v174, v175
	v_cvt_pk_bf16_f32 v175, v176, v177
	global_store_dwordx2 v170, v[174:175], s[38:39]
	v_fmamk_f32 v0, v197, 0x3b800000, v230
	v_rsq_f32_e32 v0, v0
	v_lshlrev_b32_e32 v202, 16, v188
	v_and_b32_e32 v203, 0xffff0000, v188
	v_lshlrev_b32_e32 v204, 16, v189
	v_and_b32_e32 v205, 0xffff0000, v189
	v_pk_mul_f32 v[198:199], v[198:199], v[0:1] op_sel_hi:[1,0]
	v_pk_mul_f32 v[200:201], v[200:201], v[0:1] op_sel_hi:[1,0]
	v_pk_mul_f32 v[198:199], v[190:191], v[198:199]
	v_pk_mul_f32 v[200:201], v[192:193], v[200:201]
	v_mul_f32_e32 v184, 0xbfb8aa3b, v202
	v_exp_f32_e32 v184, v184
	s_nop 0
	v_add_f32_e32 v184, 1.0, v184
	v_div_scale_f32 v185, s[4:5], v184, v184, v202
	v_rcp_f32_e32 v186, v185
	s_nop 0
	v_fma_f32 v187, -v185, v186, 1.0
	v_fmac_f32_e32 v186, v187, v186
	v_div_scale_f32 v187, vcc, v202, v184, v202
	v_mul_f32_e32 v206, v187, v186
	v_fma_f32 v207, -v185, v206, v187
	v_fmac_f32_e32 v206, v207, v186
	v_fma_f32 v185, -v185, v206, v187
	v_div_fmas_f32 v185, v185, v186, v206
	v_div_fixup_f32 v202, v185, v184, v202
	v_mul_f32_e32 v184, 0xbfb8aa3b, v203
	v_exp_f32_e32 v184, v184
	s_nop 0
	v_add_f32_e32 v184, 1.0, v184
	v_div_scale_f32 v185, s[4:5], v184, v184, v203
	v_rcp_f32_e32 v186, v185
	s_nop 0
	v_fma_f32 v187, -v185, v186, 1.0
	v_fmac_f32_e32 v186, v187, v186
	v_div_scale_f32 v187, vcc, v203, v184, v203
	v_mul_f32_e32 v206, v187, v186
	v_fma_f32 v207, -v185, v206, v187
	v_fmac_f32_e32 v206, v207, v186
	v_fma_f32 v185, -v185, v206, v187
	v_div_fmas_f32 v185, v185, v186, v206
	v_div_fixup_f32 v203, v185, v184, v203
	v_mul_f32_e32 v184, 0xbfb8aa3b, v204
	v_exp_f32_e32 v184, v184
	s_nop 0
	v_add_f32_e32 v184, 1.0, v184
	v_div_scale_f32 v185, s[4:5], v184, v184, v204
	v_rcp_f32_e32 v186, v185
	s_nop 0
	v_fma_f32 v187, -v185, v186, 1.0
	v_fmac_f32_e32 v186, v187, v186
	v_div_scale_f32 v187, vcc, v204, v184, v204
	v_mul_f32_e32 v206, v187, v186
	v_fma_f32 v207, -v185, v206, v187
	v_fmac_f32_e32 v206, v207, v186
	v_fma_f32 v185, -v185, v206, v187
	v_div_fmas_f32 v185, v185, v186, v206
	v_div_fixup_f32 v204, v185, v184, v204
	v_mul_f32_e32 v184, 0xbfb8aa3b, v205
	v_exp_f32_e32 v184, v184
	s_nop 0
	v_add_f32_e32 v184, 1.0, v184
	v_div_scale_f32 v185, s[4:5], v184, v184, v205
	v_rcp_f32_e32 v186, v185
	s_nop 0
	v_fma_f32 v187, -v185, v186, 1.0
	v_fmac_f32_e32 v186, v187, v186
	v_div_scale_f32 v187, vcc, v205, v184, v205
	v_mul_f32_e32 v206, v187, v186
	v_fma_f32 v207, -v185, v206, v187
	v_fmac_f32_e32 v206, v207, v186
	v_fma_f32 v185, -v185, v206, v187
	v_div_fmas_f32 v185, v185, v186, v206
	v_div_fixup_f32 v205, v185, v184, v205
	v_pk_mul_f32 v[198:199], v[202:203], v[198:199]
	v_pk_mul_f32 v[200:201], v[204:205], v[200:201]
	v_cvt_pk_bf16_f32 v198, v198, v199
	v_cvt_pk_bf16_f32 v199, v200, v201
	global_store_dwordx2 v194, v[198:199], s[38:39]
	s_mul_i32 s5, s11, 8
	s_add_i32 s10, s10, s5
	s_branch .Lp6_main
.Lp6_tail:
	s_cmp_lt_u32 s10, 0x28000
	s_cbranch_scc0 .Lp6_done
	s_mov_b32 s5, s10
	s_lshl_b32 s42, s5, 9
	s_lshr_b32 s43, s5, 2
	s_lshl_b32 s43, s43, 12
	s_and_b32 s64, s5, 3
	s_lshl_b32 s65, s64, 9
	s_add_i32 s43, s43, s65
	s_lshl_b32 s64, s64, 10
	v_add_u32_e32 v26, s42, v2
	v_add_u32_e32 v27, s43, v2
	v_add_u32_e32 v28, s64, v3
	global_load_dwordx2 v[16:17], v26, s[36:37]
	global_load_dwordx2 v[18:19], v26, s[40:41]
	global_load_dwordx2 v[20:21], v27, s[20:21]
	global_load_dwordx4 v[22:25], v28, s[74:75]
	s_waitcnt vmcnt(2)
	v_lshlrev_b32_e32 v30, 16, v16
	v_and_b32_e32 v31, 0xffff0000, v16
	v_lshlrev_b32_e32 v34, 16, v18
	v_and_b32_e32 v35, 0xffff0000, v18
	v_lshlrev_b32_e32 v32, 16, v17
	v_and_b32_e32 v33, 0xffff0000, v17
	v_lshlrev_b32_e32 v36, 16, v19
	v_and_b32_e32 v37, 0xffff0000, v19
	v_pk_add_f32 v[32:33], v[32:33], v[36:37]
	v_pk_add_f32 v[30:31], v[30:31], v[34:35]
	v_pk_mul_f32 v[36:37], v[32:33], v[32:33]
	v_pk_mul_f32 v[34:35], v[30:31], v[30:31]
	v_add_f32_e32 v29, v34, v35
	v_add_f32_e32 v29, v29, v36
	v_add_f32_e32 v29, v37, v29
	ds_bpermute_b32 v34, v4, v29
	s_waitcnt lgkmcnt(0)
	v_add_f32_e32 v29, v29, v34
	ds_bpermute_b32 v34, v5, v29
	s_waitcnt lgkmcnt(0)
	v_add_f32_e32 v29, v29, v34
	ds_bpermute_b32 v34, v6, v29
	s_waitcnt lgkmcnt(0)
	v_add_f32_e32 v29, v29, v34
	ds_bpermute_b32 v34, v7, v29
	s_waitcnt lgkmcnt(0)
	v_add_f32_e32 v29, v29, v34
	ds_bpermute_b32 v34, v8, v29
	s_waitcnt lgkmcnt(0)
	v_add_f32_e32 v29, v29, v34
	ds_bpermute_b32 v34, v9, v29
	s_waitcnt lgkmcnt(0)
	v_add_f32_e32 v29, v29, v34
	s_waitcnt vmcnt(0)
	v_fmamk_f32 v0, v29, 0x3b800000, v230
	v_rsq_f32_e32 v0, v0
	v_lshlrev_b32_e32 v34, 16, v20
	v_and_b32_e32 v35, 0xffff0000, v20
	v_lshlrev_b32_e32 v36, 16, v21
	v_and_b32_e32 v37, 0xffff0000, v21
	v_pk_mul_f32 v[30:31], v[30:31], v[0:1] op_sel_hi:[1,0]
	v_pk_mul_f32 v[32:33], v[32:33], v[0:1] op_sel_hi:[1,0]
	v_pk_mul_f32 v[30:31], v[22:23], v[30:31]
	v_pk_mul_f32 v[32:33], v[24:25], v[32:33]
	v_mul_f32_e32 v16, 0xbfb8aa3b, v34
	v_exp_f32_e32 v16, v16
	s_nop 0
	v_add_f32_e32 v16, 1.0, v16
	v_div_scale_f32 v17, s[4:5], v16, v16, v34
	v_rcp_f32_e32 v18, v17
	s_nop 0
	v_fma_f32 v19, -v17, v18, 1.0
	v_fmac_f32_e32 v18, v19, v18
	v_div_scale_f32 v19, vcc, v34, v16, v34
	v_mul_f32_e32 v38, v19, v18
	v_fma_f32 v39, -v17, v38, v19
	v_fmac_f32_e32 v38, v39, v18
	v_fma_f32 v17, -v17, v38, v19
	v_div_fmas_f32 v17, v17, v18, v38
	v_div_fixup_f32 v34, v17, v16, v34
	v_mul_f32_e32 v16, 0xbfb8aa3b, v35
	v_exp_f32_e32 v16, v16
	s_nop 0
	v_add_f32_e32 v16, 1.0, v16
	v_div_scale_f32 v17, s[4:5], v16, v16, v35
	v_rcp_f32_e32 v18, v17
	s_nop 0
	v_fma_f32 v19, -v17, v18, 1.0
	v_fmac_f32_e32 v18, v19, v18
	v_div_scale_f32 v19, vcc, v35, v16, v35
	v_mul_f32_e32 v38, v19, v18
	v_fma_f32 v39, -v17, v38, v19
	v_fmac_f32_e32 v38, v39, v18
	v_fma_f32 v17, -v17, v38, v19
	v_div_fmas_f32 v17, v17, v18, v38
	v_div_fixup_f32 v35, v17, v16, v35
	v_mul_f32_e32 v16, 0xbfb8aa3b, v36
	v_exp_f32_e32 v16, v16
	s_nop 0
	v_add_f32_e32 v16, 1.0, v16
	v_div_scale_f32 v17, s[4:5], v16, v16, v36
	v_rcp_f32_e32 v18, v17
	s_nop 0
	v_fma_f32 v19, -v17, v18, 1.0
	v_fmac_f32_e32 v18, v19, v18
	v_div_scale_f32 v19, vcc, v36, v16, v36
	v_mul_f32_e32 v38, v19, v18
	v_fma_f32 v39, -v17, v38, v19
	v_fmac_f32_e32 v38, v39, v18
	v_fma_f32 v17, -v17, v38, v19
	v_div_fmas_f32 v17, v17, v18, v38
	v_div_fixup_f32 v36, v17, v16, v36
	v_mul_f32_e32 v16, 0xbfb8aa3b, v37
	v_exp_f32_e32 v16, v16
	s_nop 0
	v_add_f32_e32 v16, 1.0, v16
	v_div_scale_f32 v17, s[4:5], v16, v16, v37
	v_rcp_f32_e32 v18, v17
	s_nop 0
	v_fma_f32 v19, -v17, v18, 1.0
	v_fmac_f32_e32 v18, v19, v18
	v_div_scale_f32 v19, vcc, v37, v16, v37
	v_mul_f32_e32 v38, v19, v18
	v_fma_f32 v39, -v17, v38, v19
	v_fmac_f32_e32 v38, v39, v18
	v_fma_f32 v17, -v17, v38, v19
	v_div_fmas_f32 v17, v17, v18, v38
	v_div_fixup_f32 v37, v17, v16, v37
	v_pk_mul_f32 v[30:31], v[34:35], v[30:31]
	v_pk_mul_f32 v[32:33], v[36:37], v[32:33]
	v_cvt_pk_bf16_f32 v30, v30, v31
	v_cvt_pk_bf16_f32 v31, v32, v33
	global_store_dwordx2 v26, v[30:31], s[38:39]
	s_add_i32 s10, s10, s11
	s_branch .Lp6_tail
.Lp6_done:
	v_readlane_b32 s64, v252, 13
	v_readlane_b32 s65, v252, 14
	v_readlane_b32 s66, v252, 15
	v_readlane_b32 s67, v252, 16
	v_readlane_b32 s68, v252, 17
	v_readlane_b32 s69, v252, 18
	v_readlane_b32 s70, v252, 19
	v_readlane_b32 s71, v252, 20
	v_readlane_b32 s72, v252, 21
	v_readlane_b32 s73, v252, 22
	v_readlane_b32 s74, v252, 23
	v_readlane_b32 s75, v252, 24
	v_readlane_b32 s76, v252, 25
	v_readlane_b32 s77, v252, 26
	v_readlane_b32 s78, v252, 27
	v_readlane_b32 s79, v252, 28

.LBB0_295:
	s_nop 0
	v_readlane_b32 s0, v254, 37
	v_readlane_b32 s1, v254, 38
	s_and_b64 vcc, exec, s[0:1]
	s_cbranch_vccz .LBB0_316
	s_mov_b32 s36, s35
	s_mov_b32 s0, s98
	s_mov_b32 s1, -1
	v_mbcnt_lo_u32_b32 v0, -1, 0
	v_mbcnt_hi_u32_b32 v0, s1, v0
	v_readlane_b32 s1, v252, 0
	v_lshl_add_u32 v158, s0, 6, v0
	s_mov_b32 s4, s1
	s_ashr_i32 s0, s1, 3
	v_readlane_b32 s5, v254, 6
	s_cmp_ge_i32 s0, s5
	s_cbranch_scc1 .LBB0_315
	s_cmpk_gt_i32 s0, 0x9f
	s_cbranch_scc1 .LBB0_315
	s_bitcmp1_b32 s0, 0
	s_cbranch_scc0 .Lp7_nostag
	s_sleep 127
	s_sleep 127
	s_sleep 127
	s_sleep 127
	s_sleep 127
	s_sleep 127
	s_sleep 127
.Lp7_nostag:
	v_bfe_i32 v3, v158, 27, 1
	v_lshlrev_b32_e32 v0, 4, v158
	v_lshrrev_b32_e32 v3, 22, v3
	v_add_u32_e32 v3, v0, v3
	v_and_b32_e32 v3, 0xfffffc00, v3
	v_ashrrev_i32_e32 v2, 31, v158
	v_sub_u32_e32 v3, v0, v3
	v_lshrrev_b32_e32 v2, 26, v2
	v_lshrrev_b32_e32 v4, 4, v3
	v_add_u32_e32 v2, v158, v2
	v_bitop3_b32 v4, v4, v3, 32 bitop3:0x6c
	v_ashrrev_i32_e32 v3, 31, v3
	v_ashrrev_i32_e32 v2, 6, v2
	v_lshrrev_b32_e32 v3, 26, v3
	v_lshlrev_b32_e32 v5, 3, v2
	v_add_u32_e32 v3, v4, v3
	v_and_b32_e32 v5, -16, v5
	v_ashrrev_i32_e32 v3, 6, v3
	v_add_u32_e32 v5, v3, v5
	v_mul_i32_i24_e32 v3, 64, v3
	v_lshlrev_b32_e32 v2, 5, v2
	v_sub_u32_e32 v3, v4, v3
	v_and_b32_e32 v2, 32, v2
	v_ashrrev_i16_sdwa v3, v232, sext(v3) dst_sel:DWORD dst_unused:UNUSED_PAD src0_sel:DWORD src1_sel:BYTE_0
	v_add_u32_sdwa v2, v2, sext(v3) dst_sel:DWORD dst_unused:UNUSED_PAD src0_sel:DWORD src1_sel:WORD_0
	v_lshlrev_b32_e32 v3, 12, v5
	v_lshl_add_u32 v159, v2, 1, v3
	v_lshlrev_b32_e32 v2, 11, v5
	v_add_u32_e32 v0, 0x2000, v0
	v_sub_u32_e32 v169, v159, v2
	v_ashrrev_i32_e32 v2, 31, v0
	v_lshrrev_b32_e32 v2, 22, v2
	v_add_u32_e32 v2, v0, v2
	v_ashrrev_i32_e32 v2, 10, v2
	v_mul_i32_i24_e32 v3, 0x400, v2
	v_sub_u32_e32 v0, v0, v3
	s_and_b32 s6, s4, 7
	v_lshrrev_b32_e32 v3, 4, v0
	s_mul_i32 s4, s6, 0xa0
	v_bitop3_b32 v0, v3, v0, 32 bitop3:0x6c
	s_add_i32 s8, s4, 0xa0
	v_readlane_b32 s40, v252, 3
	v_ashrrev_i32_e32 v4, 31, v0
	v_readlane_b32 s41, v252, 4
	s_add_u32 s9, s40, s36
	v_lshrrev_b32_e32 v4, 26, v4
	s_addc_u32 s10, s41, 0
	v_add_u32_e32 v4, v0, v4
	s_add_u32 s15, s9, 0x3739b600
	v_lshlrev_b32_e32 v3, 3, v2
	v_ashrrev_i32_e32 v5, 6, v4
	v_and_b32_e32 v4, 0xc0, v4
	s_addc_u32 s16, s10, 0
	v_and_b32_e32 v3, -16, v3
	v_lshlrev_b32_e32 v2, 5, v2
	v_sub_u32_e32 v0, v0, v4
	s_add_u32 s17, s9, 0x1899b600
	v_add_u32_e32 v3, v5, v3
	v_and_b32_e32 v2, 32, v2
	v_ashrrev_i16_sdwa v0, v232, sext(v0) dst_sel:DWORD dst_unused:UNUSED_PAD src0_sel:DWORD src1_sel:BYTE_0
	s_addc_u32 s18, s10, 0
	v_add_u32_sdwa v0, v2, sext(v0) dst_sel:DWORD dst_unused:UNUSED_PAD src0_sel:DWORD src1_sel:WORD_0
	v_lshlrev_b32_e32 v2, 12, v3
	s_add_u32 s48, s9, 0x175b600
	v_lshl_add_u32 v233, v0, 1, v2
	v_lshlrev_b32_e32 v0, 11, v3
	v_and_b32_e32 v3, 15, v158
	v_lshlrev_b32_e32 v4, 2, v158
	s_addc_u32 s49, s10, 0
	s_lshr_b32 s50, s1, 3
	v_sub_u32_e32 v162, v233, v0
	v_and_b32_e32 v0, 48, v158
	v_lshlrev_b32_e32 v2, 6, v3
	v_and_b32_e32 v4, 32, v4
	v_lshrrev_b32_e32 v5, 1, v158
	s_movk_i32 s1, 0x60
	v_bitop3_b32 v163, v2, v4, v0 bitop3:0x36
	v_ashrrev_i32_e32 v0, 2, v158
	v_ashrrev_i32_e32 v2, 5, v158
	v_and_or_b32 v3, v5, s1, v3
	s_movk_i32 s1, 0x210
	v_and_b32_e32 v130, 0xffffffc0, v0
	v_lshrrev_b32_e32 v0, 2, v158
	v_mul_u32_u24_e32 v5, 0x210, v3
	v_mad_u32_u24 v10, v3, s1, v235
	v_mad_u32_u24 v11, v3, s1, v231
	v_ashrrev_i32_e32 v3, 31, v2
	s_add_i32 s51, s4, s0
	v_and_b32_e32 v0, 12, v0
	v_and_b32_e32 v7, 31, v158
	v_lshlrev_b64 v[132:133], 13, v[2:3]
	s_mov_b64 s[4:5], 0x20000
	v_or_b32_e32 v6, v130, v0
	v_lshlrev_b32_e32 v8, 4, v7
	v_lshl_add_u64 v[134:135], v[132:133], 0, s[4:5]
	s_mov_b64 s[4:5], 0x40000
	v_mul_lo_u32 v2, v2, s1
	s_mul_i32 s1, s6, 0x1400
	s_lshl_b32 s0, s0, 5
	v_readlane_b32 s64, v252, 13
	v_lshlrev_b32_e32 v4, 3, v7
	v_add_u32_e32 v9, 0, v8
	v_lshl_add_u32 v6, v6, 1, 0
	v_lshl_add_u64 v[136:137], v[132:133], 0, s[4:5]
	s_mov_b64 s[4:5], 0x60000
	s_add_i32 s52, s1, s0
	v_lshl_or_b32 v160, v7, 5, v132
	v_mov_b32_e32 v161, v133
	v_readlane_b32 s78, v252, 27
	v_readlane_b32 s79, v252, 28
	s_add_i32 s0, 0, 0x8400
	s_mov_b32 s37, s35
	v_ashrrev_i32_e32 v131, 31, v130
	v_lshl_add_u64 v[138:139], v[132:133], 0, s[4:5]
	v_lshl_add_u64 v[156:157], s[78:79], 0, v[160:161]
	v_add3_u32 v164, v2, v8, s0
	v_lshlrev_b32_e32 v144, 2, v0
	v_add_u32_e32 v165, v6, v5
	v_add_u32_e32 v166, v6, v10
	v_add_u32_e32 v167, v6, v11
	v_lshlrev_b32_e32 v146, 2, v4
	v_add_u32_e32 v168, v9, v2
	v_readlane_b32 s42, v252, 5
	v_readlane_b32 s43, v252, 6
	v_readlane_b32 s65, v252, 14
	v_readlane_b32 s66, v252, 15
	v_readlane_b32 s67, v252, 16
	v_readlane_b32 s68, v252, 17
	v_readlane_b32 s69, v252, 18
	v_readlane_b32 s70, v252, 19
	v_readlane_b32 s71, v252, 20
	v_readlane_b32 s72, v252, 21
	v_readlane_b32 s73, v252, 22
	v_readlane_b32 s74, v252, 23
	v_readlane_b32 s75, v252, 24
	v_readlane_b32 s76, v252, 25
	v_readlane_b32 s77, v252, 26

.LBB0_307:
	s_add_i32 s20, s38, 0xffffe000
	s_ashr_i32 s6, s20, 12
	s_cmp_gt_i32 s5, 31
	s_cselect_b64 s[0:1], -1, 0
	s_mulk_i32 s6, 0x1800
	s_and_b64 vcc, s[0:1], exec
	s_cselect_b32 s0, s6, 0xc000
	s_ashr_i32 s1, s0, 31
	s_lshl_b64 s[0:1], s[0:1], 2
	s_add_u32 s0, s9, s0
	s_addc_u32 s1, s10, s1
	s_lshl_b32 s13, s4, 2
	s_add_u32 s0, s0, s13
	s_addc_u32 s1, s1, 0
	v_lshl_add_u64 v[140:141], v[130:131], 2, s[0:1]
	v_mov_b32_e32 v145, v1
	v_lshl_add_u64 v[140:141], v[140:141], 0, v[144:145]
	s_mov_b64 s[0:1], 0x4000
	v_lshl_add_u64 v[148:149], v[140:141], 0, s[0:1]
	s_movk_i32 s0, 0x4000
	v_add_co_u32_e64 v140, s[0:1], s0, v140
	s_waitcnt vmcnt(0)
	s_nop 0
	v_addc_co_u32_e64 v141, s[0:1], 0, v141, s[0:1]
	global_load_dwordx4 v[170:173], v[140:141], off
	global_load_dwordx4 v[174:177], v[148:149], off offset:64
	global_load_dwordx4 v[178:181], v[148:149], off offset:128
	global_load_dwordx4 v[182:185], v[148:149], off offset:192
	global_load_dwordx4 v[186:189], v[148:149], off offset:512
	global_load_dwordx4 v[190:193], v[148:149], off offset:576
	global_load_dwordx4 v[194:197], v[148:149], off offset:640
	global_load_dwordx4 v[198:201], v[148:149], off offset:704
	s_barrier
	v_add_u32_e32 v0, 0x2000, v165
	s_mov_b64 s[6:7], -1
	s_waitcnt vmcnt(0)
	v_pk_mul_f32 v[120:121], v[120:121], v[172:173]
	v_pk_mul_f32 v[118:119], v[118:119], v[170:171]
	v_pk_mul_f32 v[116:117], v[116:117], v[172:173]
	v_pk_mul_f32 v[114:115], v[114:115], v[170:171]
	v_cvt_pk_bf16_f32 v121, v120, v121
	v_cvt_pk_bf16_f32 v120, v118, v119
	v_cvt_pk_bf16_f32 v119, v116, v117
	v_cvt_pk_bf16_f32 v118, v114, v115
	v_pk_mul_f32 v[114:115], v[128:129], v[172:173]
	v_pk_mul_f32 v[116:117], v[126:127], v[170:171]
	v_cvt_pk_bf16_f32 v127, v114, v115
	v_cvt_pk_bf16_f32 v126, v116, v117
	v_pk_mul_f32 v[114:115], v[124:125], v[172:173]
	v_pk_mul_f32 v[116:117], v[122:123], v[170:171]
	v_cvt_pk_bf16_f32 v123, v114, v115
	v_cvt_pk_bf16_f32 v122, v116, v117
	s_waitcnt vmcnt(0)
	v_pk_mul_f32 v[100:101], v[100:101], v[176:177]
	v_pk_mul_f32 v[98:99], v[98:99], v[174:175]
	v_cvt_pk_bf16_f32 v101, v100, v101
	v_cvt_pk_bf16_f32 v100, v98, v99
	ds_write2_b64 v0, v[118:119], v[100:101] offset0:32 offset1:36
	v_pk_mul_f32 v[98:99], v[112:113], v[176:177]
	v_pk_mul_f32 v[100:101], v[110:111], v[174:175]
	v_cvt_pk_bf16_f32 v99, v98, v99
	v_cvt_pk_bf16_f32 v98, v100, v101
	ds_write2_b64 v166, v[126:127], v[98:99] offset1:4
	v_pk_mul_f32 v[98:99], v[108:109], v[176:177]
	v_pk_mul_f32 v[100:101], v[106:107], v[174:175]
	v_cvt_pk_bf16_f32 v99, v98, v99
	v_cvt_pk_bf16_f32 v98, v100, v101
	ds_write2_b64 v167, v[122:123], v[98:99] offset1:4
	v_pk_mul_f32 v[104:105], v[104:105], v[176:177]
	v_pk_mul_f32 v[102:103], v[102:103], v[174:175]
	v_cvt_pk_bf16_f32 v105, v104, v105
	v_cvt_pk_bf16_f32 v104, v102, v103
	ds_write2_b64 v165, v[120:121], v[104:105] offset1:4
	s_waitcnt vmcnt(0)
	v_pk_mul_f32 v[88:89], v[88:89], v[180:181]
	v_pk_mul_f32 v[86:87], v[86:87], v[178:179]
	v_pk_mul_f32 v[84:85], v[84:85], v[180:181]
	v_pk_mul_f32 v[82:83], v[82:83], v[178:179]
	v_cvt_pk_bf16_f32 v89, v88, v89
	v_cvt_pk_bf16_f32 v88, v86, v87
	v_cvt_pk_bf16_f32 v87, v84, v85
	v_cvt_pk_bf16_f32 v86, v82, v83
	v_pk_mul_f32 v[82:83], v[96:97], v[180:181]
	v_pk_mul_f32 v[84:85], v[94:95], v[178:179]
	v_cvt_pk_bf16_f32 v95, v82, v83
	v_cvt_pk_bf16_f32 v94, v84, v85
	v_pk_mul_f32 v[82:83], v[92:93], v[180:181]
	v_pk_mul_f32 v[84:85], v[90:91], v[178:179]
	v_cvt_pk_bf16_f32 v91, v82, v83
	v_cvt_pk_bf16_f32 v90, v84, v85
	s_waitcnt vmcnt(0)
	v_pk_mul_f32 v[68:69], v[68:69], v[184:185]
	v_pk_mul_f32 v[66:67], v[66:67], v[182:183]
	v_cvt_pk_bf16_f32 v69, v68, v69
	v_cvt_pk_bf16_f32 v68, v66, v67
	ds_write2_b64 v0, v[86:87], v[68:69] offset0:40 offset1:44
	v_pk_mul_f32 v[66:67], v[80:81], v[184:185]
	v_pk_mul_f32 v[68:69], v[78:79], v[182:183]
	v_cvt_pk_bf16_f32 v67, v66, v67
	v_cvt_pk_bf16_f32 v66, v68, v69
	ds_write2_b64 v166, v[94:95], v[66:67] offset0:8 offset1:12
	v_pk_mul_f32 v[66:67], v[76:77], v[184:185]
	v_pk_mul_f32 v[68:69], v[74:75], v[182:183]
	v_cvt_pk_bf16_f32 v67, v66, v67
	v_cvt_pk_bf16_f32 v66, v68, v69
	ds_write2_b64 v167, v[90:91], v[66:67] offset0:8 offset1:12
	v_pk_mul_f32 v[72:73], v[72:73], v[184:185]
	v_pk_mul_f32 v[70:71], v[70:71], v[182:183]
	v_cvt_pk_bf16_f32 v73, v72, v73
	v_cvt_pk_bf16_f32 v72, v70, v71
	ds_write2_b64 v165, v[88:89], v[72:73] offset0:8 offset1:12
	s_waitcnt vmcnt(0)
	v_pk_mul_f32 v[56:57], v[56:57], v[188:189]
	v_pk_mul_f32 v[54:55], v[54:55], v[186:187]
	v_pk_mul_f32 v[52:53], v[52:53], v[188:189]
	v_pk_mul_f32 v[50:51], v[50:51], v[186:187]
	v_cvt_pk_bf16_f32 v57, v56, v57
	v_cvt_pk_bf16_f32 v56, v54, v55
	v_cvt_pk_bf16_f32 v55, v52, v53
	v_cvt_pk_bf16_f32 v54, v50, v51
	v_pk_mul_f32 v[50:51], v[64:65], v[188:189]
	v_pk_mul_f32 v[52:53], v[62:63], v[186:187]
	v_cvt_pk_bf16_f32 v63, v50, v51
	v_cvt_pk_bf16_f32 v62, v52, v53
	v_pk_mul_f32 v[50:51], v[60:61], v[188:189]
	v_pk_mul_f32 v[52:53], v[58:59], v[186:187]
	v_cvt_pk_bf16_f32 v59, v50, v51
	v_cvt_pk_bf16_f32 v58, v52, v53
	s_waitcnt vmcnt(0)
	v_pk_mul_f32 v[40:41], v[40:41], v[192:193]
	v_pk_mul_f32 v[38:39], v[38:39], v[190:191]
	v_cvt_pk_bf16_f32 v41, v40, v41
	v_cvt_pk_bf16_f32 v40, v38, v39
	ds_write2_b64 v165, v[56:57], v[40:41] offset0:32 offset1:36
	v_pk_mul_f32 v[36:37], v[36:37], v[192:193]
	v_pk_mul_f32 v[34:35], v[34:35], v[190:191]
	v_cvt_pk_bf16_f32 v37, v36, v37
	v_cvt_pk_bf16_f32 v36, v34, v35
	ds_write2_b64 v0, v[54:55], v[36:37] offset0:64 offset1:68
	v_pk_mul_f32 v[34:35], v[48:49], v[192:193]
	v_pk_mul_f32 v[36:37], v[46:47], v[190:191]
	v_cvt_pk_bf16_f32 v35, v34, v35
	v_cvt_pk_bf16_f32 v34, v36, v37
	ds_write2_b64 v166, v[62:63], v[34:35] offset0:32 offset1:36
	v_pk_mul_f32 v[34:35], v[44:45], v[192:193]
	v_pk_mul_f32 v[36:37], v[42:43], v[190:191]
	v_cvt_pk_bf16_f32 v35, v34, v35
	v_cvt_pk_bf16_f32 v34, v36, v37
	ds_write2_b64 v167, v[58:59], v[34:35] offset0:32 offset1:36
	s_waitcnt vmcnt(0)
	v_pk_mul_f32 v[20:21], v[20:21], v[196:197]
	v_pk_mul_f32 v[18:19], v[18:19], v[194:195]
	v_pk_mul_f32 v[24:25], v[24:25], v[196:197]
	v_cvt_pk_bf16_f32 v35, v20, v21
	v_cvt_pk_bf16_f32 v34, v18, v19
	v_pk_mul_f32 v[18:19], v[32:33], v[196:197]
	v_pk_mul_f32 v[20:21], v[30:31], v[194:195]
	v_pk_mul_f32 v[22:23], v[22:23], v[194:195]
	v_cvt_pk_bf16_f32 v37, v24, v25
	v_cvt_pk_bf16_f32 v25, v18, v19
	v_cvt_pk_bf16_f32 v24, v20, v21
	v_pk_mul_f32 v[18:19], v[28:29], v[196:197]
	v_pk_mul_f32 v[20:21], v[26:27], v[194:195]
	v_cvt_pk_bf16_f32 v36, v22, v23
	v_cvt_pk_bf16_f32 v23, v18, v19
	v_cvt_pk_bf16_f32 v22, v20, v21
	s_waitcnt vmcnt(0)
	v_pk_mul_f32 v[4:5], v[4:5], v[200:201]
	v_pk_mul_f32 v[2:3], v[2:3], v[198:199]
	v_cvt_pk_bf16_f32 v5, v4, v5
	v_cvt_pk_bf16_f32 v4, v2, v3
	ds_write2_b64 v0, v[34:35], v[4:5] offset0:72 offset1:76
	v_pk_mul_f32 v[2:3], v[16:17], v[200:201]
	v_pk_mul_f32 v[4:5], v[14:15], v[198:199]
	v_cvt_pk_bf16_f32 v3, v2, v3
	v_cvt_pk_bf16_f32 v2, v4, v5
	v_pk_mul_f32 v[12:13], v[12:13], v[200:201]
	v_pk_mul_f32 v[10:11], v[10:11], v[198:199]
	ds_write2_b64 v166, v[24:25], v[2:3] offset0:40 offset1:44
	v_pk_mul_f32 v[2:3], v[8:9], v[200:201]
	v_pk_mul_f32 v[4:5], v[6:7], v[198:199]
	v_cvt_pk_bf16_f32 v13, v12, v13
	v_cvt_pk_bf16_f32 v12, v10, v11
	v_cvt_pk_bf16_f32 v3, v2, v3
	v_cvt_pk_bf16_f32 v2, v4, v5
	ds_write2_b64 v165, v[36:37], v[12:13] offset0:40 offset1:44
	ds_write2_b64 v167, v[22:23], v[2:3] offset0:40 offset1:44
	s_cbranch_vccz .LBB0_309
	s_ashr_i32 s21, s20, 31
	v_readlane_b32 s64, v254, 19
	s_lshl_b64 s[0:1], s[20:21], 13
	v_readlane_b32 s66, v254, 21
	v_readlane_b32 s67, v254, 22
	s_add_u32 s0, s66, s0
	v_readlane_b32 s65, v254, 20
	v_readlane_b32 s68, v254, 23
	v_readlane_b32 s69, v254, 24
	v_readlane_b32 s70, v254, 25
	v_readlane_b32 s71, v254, 26
	v_readlane_b32 s72, v254, 27
	v_readlane_b32 s73, v254, 28
	v_readlane_b32 s74, v254, 29
	v_readlane_b32 s75, v254, 30
	v_readlane_b32 s76, v254, 31
	v_readlane_b32 s77, v254, 32
	v_readlane_b32 s78, v254, 33
	v_readlane_b32 s79, v254, 34
	s_addc_u32 s1, s67, s1
	s_lshl_b64 s[4:5], s[38:39], 13
	s_mov_b64 s[6:7], 0

.LBB0_311:
	s_and_b32 s6, s50, 7
	s_lshl_b32 s6, s6, 8
	s_lshl_b32 s34, s11, 10
	s_add_u32 s20, s0, s13
	s_addc_u32 s21, s1, 0
	v_mov_b32_e32 v147, v1
	v_lshl_add_u64 v[2:3], s[20:21], 0, v[146:147]
	v_lshl_add_u64 v[4:5], v[2:3], 0, v[132:133]
	v_mov_b64_e32 v[202:203], v[4:5]
	global_load_dwordx4 v[18:21], v[4:5], off offset:16
	global_load_dwordx4 v[22:25], v[4:5], off
	v_lshl_add_u64 v[6:7], v[2:3], 0, v[134:135]
	global_load_dwordx4 v[26:29], v[6:7], off offset:16
	global_load_dwordx4 v[30:33], v[6:7], off
	v_lshl_add_u64 v[8:9], v[2:3], 0, v[136:137]
	global_load_dwordx4 v[10:13], v[8:9], off offset:16
	global_load_dwordx4 v[34:37], v[8:9], off
	v_readlane_b32 s64, v252, 13
	v_readlane_b32 s78, v252, 27
	v_readlane_b32 s79, v252, 28
	s_add_u32 s4, s78, s4
	s_addc_u32 s5, s79, s5
	s_add_u32 s4, s4, s13
	s_addc_u32 s5, s5, 0
	v_lshl_add_u64 v[38:39], v[2:3], 0, v[138:139]
	v_lshl_add_u64 v[2:3], s[4:5], 0, v[146:147]
	v_lshl_add_u64 v[42:43], v[2:3], 0, v[132:133]
	v_mov_b64_e32 v[204:205], v[42:43]
	v_lshl_add_u64 v[44:45], v[2:3], 0, v[134:135]
	v_lshl_add_u64 v[16:17], v[2:3], 0, v[136:137]
	v_lshl_add_u64 v[14:15], v[2:3], 0, v[138:139]
	global_load_dwordx4 v[2:5], v[38:39], off offset:16
	global_load_dwordx4 v[6:9], v[38:39], off
	s_mov_b64 s[20:21], 0x80000
	v_lshl_add_u64 v[206:207], v[202:203], 0, s[20:21]
	global_load_dwordx4 v[48:51], v[206:207], off
	global_load_dwordx4 v[52:55], v[206:207], off offset:16
	s_add_u32 s20, s20, 0x20000
	v_lshl_add_u64 v[206:207], v[202:203], 0, s[20:21]
	global_load_dwordx4 v[56:59], v[206:207], off
	global_load_dwordx4 v[60:63], v[206:207], off offset:16
	s_add_u32 s20, s20, 0x20000
	v_lshl_add_u64 v[206:207], v[202:203], 0, s[20:21]
	global_load_dwordx4 v[64:67], v[206:207], off
	global_load_dwordx4 v[68:71], v[206:207], off offset:16
	s_add_u32 s20, s20, 0x20000
	v_lshl_add_u64 v[206:207], v[202:203], 0, s[20:21]
	global_load_dwordx4 v[72:75], v[206:207], off
	global_load_dwordx4 v[76:79], v[206:207], off offset:16
	s_add_u32 s20, s20, 0x20000
	v_lshl_add_u64 v[206:207], v[202:203], 0, s[20:21]
	global_load_dwordx4 v[80:83], v[206:207], off
	global_load_dwordx4 v[84:87], v[206:207], off offset:16
	s_add_u32 s20, s20, 0x20000
	v_lshl_add_u64 v[206:207], v[202:203], 0, s[20:21]
	global_load_dwordx4 v[88:91], v[206:207], off
	global_load_dwordx4 v[92:95], v[206:207], off offset:16
	s_add_u32 s20, s20, 0x20000
	v_lshl_add_u64 v[206:207], v[202:203], 0, s[20:21]
	global_load_dwordx4 v[96:99], v[206:207], off
	global_load_dwordx4 v[100:103], v[206:207], off offset:16
	s_add_u32 s20, s20, 0x20000
	v_lshl_add_u64 v[206:207], v[202:203], 0, s[20:21]
	global_load_dwordx4 v[104:107], v[206:207], off
	global_load_dwordx4 v[108:111], v[206:207], off offset:16
	s_add_u32 s20, s20, 0x20000
	v_lshl_add_u64 v[206:207], v[202:203], 0, s[20:21]
	global_load_dwordx4 v[112:115], v[206:207], off
	global_load_dwordx4 v[116:119], v[206:207], off offset:16
	s_add_u32 s20, s20, 0x20000
	v_lshl_add_u64 v[206:207], v[202:203], 0, s[20:21]
	global_load_dwordx4 v[120:123], v[206:207], off
	global_load_dwordx4 v[124:127], v[206:207], off offset:16
	s_add_u32 s20, s20, 0x20000
	v_lshl_add_u64 v[206:207], v[202:203], 0, s[20:21]
	global_load_dwordx4 v[210:213], v[206:207], off
	global_load_dwordx4 v[214:217], v[206:207], off offset:16
	s_add_u32 s20, s20, 0x20000
	v_lshl_add_u64 v[206:207], v[202:203], 0, s[20:21]
	global_load_dwordx4 v[218:221], v[206:207], off
	global_load_dwordx4 v[226:229], v[206:207], off offset:16
	s_add_u32 s20, s20, 0x20000
	s_waitcnt lgkmcnt(0)
	s_barrier
	ds_read_b128 v[38:41], v168
	s_lshl_b32 s4, s53, 8
	s_and_b32 s4, s4, 0xfffff800
	s_or_b32 s4, s4, s6
	s_ashr_i32 s5, s4, 31
	s_waitcnt lgkmcnt(0)
	v_lshlrev_b32_e32 v46, 16, v38
	v_and_b32_e32 v47, 0xffff0000, v38
	v_lshlrev_b32_e32 v38, 16, v39
	v_and_b32_e32 v39, 0xffff0000, v39
	s_lshl_b64 s[4:5], s[4:5], 13
	s_or_b32 s4, s4, s34
	v_mov_b32_e32 v0, v164
	s_mov_b32 s6, 0x80000
	s_mov_b32 s7, 0xa0000
	s_mov_b32 s11, 0xc0000
	s_mov_b32 s13, 0xe0000
	s_mov_b64 s[20:21], 0x80000
	v_readlane_b32 s65, v252, 14
	v_readlane_b32 s66, v252, 15
	v_readlane_b32 s67, v252, 16
	v_readlane_b32 s68, v252, 17
	v_readlane_b32 s69, v252, 18
	v_readlane_b32 s70, v252, 19
	v_readlane_b32 s71, v252, 20
	v_readlane_b32 s72, v252, 21
	v_readlane_b32 s73, v252, 22
	v_readlane_b32 s74, v252, 23
	v_readlane_b32 s75, v252, 24
	v_readlane_b32 s76, v252, 25
	v_readlane_b32 s77, v252, 26
	s_waitcnt vmcnt(30)
	v_pk_add_f32 v[24:25], v[24:25], v[38:39]
	v_lshlrev_b32_e32 v38, 16, v40
	v_and_b32_e32 v39, 0xffff0000, v40
	v_pk_add_f32 v[22:23], v[22:23], v[46:47]
	v_pk_add_f32 v[18:19], v[18:19], v[38:39]
	v_lshlrev_b32_e32 v38, 16, v41
	v_and_b32_e32 v39, 0xffff0000, v41
	v_pk_add_f32 v[20:21], v[20:21], v[38:39]
	global_store_dwordx4 v[42:43], v[22:25], off
	global_store_dwordx4 v[42:43], v[18:21], off offset:16
	ds_read_b128 v[18:21], v168 offset:8448
	s_waitcnt lgkmcnt(0)
	v_lshlrev_b32_e32 v22, 16, v18
	v_and_b32_e32 v23, 0xffff0000, v18
	v_lshlrev_b32_e32 v18, 16, v19
	v_and_b32_e32 v19, 0xffff0000, v19
	s_waitcnt vmcnt(30)
	v_pk_add_f32 v[22:23], v[30:31], v[22:23]
	v_pk_add_f32 v[24:25], v[32:33], v[18:19]
	v_lshlrev_b32_e32 v18, 16, v20
	v_and_b32_e32 v19, 0xffff0000, v20
	v_lshlrev_b32_e32 v20, 16, v21
	v_and_b32_e32 v21, 0xffff0000, v21
	v_pk_add_f32 v[18:19], v[26:27], v[18:19]
	v_pk_add_f32 v[20:21], v[28:29], v[20:21]
	global_store_dwordx4 v[44:45], v[22:25], off
	global_store_dwordx4 v[44:45], v[18:21], off offset:16
	ds_read_b128 v[18:21], v168 offset:16896
	s_waitcnt lgkmcnt(0)
	v_lshlrev_b32_e32 v22, 16, v18
	v_and_b32_e32 v23, 0xffff0000, v18
	v_lshlrev_b32_e32 v18, 16, v19
	v_and_b32_e32 v19, 0xffff0000, v19
	s_waitcnt vmcnt(30)
	v_pk_add_f32 v[24:25], v[36:37], v[18:19]
	v_lshlrev_b32_e32 v18, 16, v20
	v_and_b32_e32 v19, 0xffff0000, v20
	v_pk_add_f32 v[22:23], v[34:35], v[22:23]
	v_pk_add_f32 v[10:11], v[10:11], v[18:19]
	v_lshlrev_b32_e32 v18, 16, v21
	v_and_b32_e32 v19, 0xffff0000, v21
	v_pk_add_f32 v[12:13], v[12:13], v[18:19]
	global_store_dwordx4 v[16:17], v[22:25], off
	global_store_dwordx4 v[16:17], v[10:13], off offset:16
	ds_read_b128 v[10:13], v168 offset:25344
	s_waitcnt lgkmcnt(0)
	v_lshlrev_b32_e32 v16, 16, v10
	v_and_b32_e32 v17, 0xffff0000, v10
	v_lshlrev_b32_e32 v10, 16, v11
	v_and_b32_e32 v11, 0xffff0000, v11
	s_waitcnt vmcnt(30)
	v_pk_add_f32 v[8:9], v[8:9], v[10:11]
	v_lshlrev_b32_e32 v10, 16, v12
	v_and_b32_e32 v11, 0xffff0000, v12
	v_pk_add_f32 v[2:3], v[2:3], v[10:11]
	v_lshlrev_b32_e32 v10, 16, v13
	v_and_b32_e32 v11, 0xffff0000, v13
	v_pk_add_f32 v[6:7], v[6:7], v[16:17]
	v_pk_add_f32 v[4:5], v[4:5], v[10:11]
	global_store_dwordx4 v[14:15], v[6:9], off
	global_store_dwordx4 v[14:15], v[2:5], off offset:16
	s_nop 1
	v_add_u32_e32 v208, 0x10800, v168
	s_mov_b64 s[20:21], 0x80000
	ds_read_b128 v[10:13], v168 offset:33792
	v_lshl_add_u64 v[206:207], v[204:205], 0, s[20:21]
	s_add_u32 s20, s20, 0x20000
	s_waitcnt lgkmcnt(0)
	v_lshlrev_b32_e32 v18, 16, v10
	v_and_b32_e32 v19, 0xffff0000, v10
	v_lshlrev_b32_e32 v20, 16, v11
	v_and_b32_e32 v21, 0xffff0000, v11
	v_lshlrev_b32_e32 v22, 16, v12
	v_and_b32_e32 v23, 0xffff0000, v12
	v_lshlrev_b32_e32 v24, 16, v13
	v_and_b32_e32 v25, 0xffff0000, v13
	s_waitcnt vmcnt(30)
	v_pk_add_f32 v[48:49], v[48:49], v[18:19]
	v_pk_add_f32 v[50:51], v[50:51], v[20:21]
	v_pk_add_f32 v[52:53], v[52:53], v[22:23]
	v_pk_add_f32 v[54:55], v[54:55], v[24:25]
	global_store_dwordx4 v[206:207], v[48:51], off
	global_store_dwordx4 v[206:207], v[52:55], off offset:16
	ds_read_b128 v[10:13], v168 offset:42240
	v_lshl_add_u64 v[206:207], v[204:205], 0, s[20:21]
	s_add_u32 s20, s20, 0x20000
	s_waitcnt lgkmcnt(0)
	v_lshlrev_b32_e32 v18, 16, v10
	v_and_b32_e32 v19, 0xffff0000, v10
	v_lshlrev_b32_e32 v20, 16, v11
	v_and_b32_e32 v21, 0xffff0000, v11
	v_lshlrev_b32_e32 v22, 16, v12
	v_and_b32_e32 v23, 0xffff0000, v12
	v_lshlrev_b32_e32 v24, 16, v13
	v_and_b32_e32 v25, 0xffff0000, v13
	s_waitcnt vmcnt(30)
	v_pk_add_f32 v[56:57], v[56:57], v[18:19]
	v_pk_add_f32 v[58:59], v[58:59], v[20:21]
	v_pk_add_f32 v[60:61], v[60:61], v[22:23]
	v_pk_add_f32 v[62:63], v[62:63], v[24:25]
	global_store_dwordx4 v[206:207], v[56:59], off
	global_store_dwordx4 v[206:207], v[60:63], off offset:16
	ds_read_b128 v[10:13], v168 offset:50688
	v_lshl_add_u64 v[206:207], v[204:205], 0, s[20:21]
	s_add_u32 s20, s20, 0x20000
	s_waitcnt lgkmcnt(0)
	v_lshlrev_b32_e32 v18, 16, v10
	v_and_b32_e32 v19, 0xffff0000, v10
	v_lshlrev_b32_e32 v20, 16, v11
	v_and_b32_e32 v21, 0xffff0000, v11
	v_lshlrev_b32_e32 v22, 16, v12
	v_and_b32_e32 v23, 0xffff0000, v12
	v_lshlrev_b32_e32 v24, 16, v13
	v_and_b32_e32 v25, 0xffff0000, v13
	s_waitcnt vmcnt(30)
	v_pk_add_f32 v[64:65], v[64:65], v[18:19]
	v_pk_add_f32 v[66:67], v[66:67], v[20:21]
	v_pk_add_f32 v[68:69], v[68:69], v[22:23]
	v_pk_add_f32 v[70:71], v[70:71], v[24:25]
	global_store_dwordx4 v[206:207], v[64:67], off
	global_store_dwordx4 v[206:207], v[68:71], off offset:16
	ds_read_b128 v[10:13], v168 offset:59136
	v_lshl_add_u64 v[206:207], v[204:205], 0, s[20:21]
	s_add_u32 s20, s20, 0x20000
	s_waitcnt lgkmcnt(0)
	v_lshlrev_b32_e32 v18, 16, v10
	v_and_b32_e32 v19, 0xffff0000, v10
	v_lshlrev_b32_e32 v20, 16, v11
	v_and_b32_e32 v21, 0xffff0000, v11
	v_lshlrev_b32_e32 v22, 16, v12
	v_and_b32_e32 v23, 0xffff0000, v12
	v_lshlrev_b32_e32 v24, 16, v13
	v_and_b32_e32 v25, 0xffff0000, v13
	s_waitcnt vmcnt(30)
	v_pk_add_f32 v[72:73], v[72:73], v[18:19]
	v_pk_add_f32 v[74:75], v[74:75], v[20:21]
	v_pk_add_f32 v[76:77], v[76:77], v[22:23]
	v_pk_add_f32 v[78:79], v[78:79], v[24:25]
	global_store_dwordx4 v[206:207], v[72:75], off
	global_store_dwordx4 v[206:207], v[76:79], off offset:16
	ds_read_b128 v[10:13], v208
	v_lshl_add_u64 v[206:207], v[204:205], 0, s[20:21]
	s_add_u32 s20, s20, 0x20000
	s_waitcnt lgkmcnt(0)
	v_lshlrev_b32_e32 v18, 16, v10
	v_and_b32_e32 v19, 0xffff0000, v10
	v_lshlrev_b32_e32 v20, 16, v11
	v_and_b32_e32 v21, 0xffff0000, v11
	v_lshlrev_b32_e32 v22, 16, v12
	v_and_b32_e32 v23, 0xffff0000, v12
	v_lshlrev_b32_e32 v24, 16, v13
	v_and_b32_e32 v25, 0xffff0000, v13
	s_waitcnt vmcnt(30)
	v_pk_add_f32 v[80:81], v[80:81], v[18:19]
	v_pk_add_f32 v[82:83], v[82:83], v[20:21]
	v_pk_add_f32 v[84:85], v[84:85], v[22:23]
	v_pk_add_f32 v[86:87], v[86:87], v[24:25]
	global_store_dwordx4 v[206:207], v[80:83], off
	global_store_dwordx4 v[206:207], v[84:87], off offset:16
	ds_read_b128 v[10:13], v208 offset:8448
	v_lshl_add_u64 v[206:207], v[204:205], 0, s[20:21]
	s_add_u32 s20, s20, 0x20000
	s_waitcnt lgkmcnt(0)
	v_lshlrev_b32_e32 v18, 16, v10
	v_and_b32_e32 v19, 0xffff0000, v10
	v_lshlrev_b32_e32 v20, 16, v11
	v_and_b32_e32 v21, 0xffff0000, v11
	v_lshlrev_b32_e32 v22, 16, v12
	v_and_b32_e32 v23, 0xffff0000, v12
	v_lshlrev_b32_e32 v24, 16, v13
	v_and_b32_e32 v25, 0xffff0000, v13
	s_waitcnt vmcnt(30)
	v_pk_add_f32 v[88:89], v[88:89], v[18:19]
	v_pk_add_f32 v[90:91], v[90:91], v[20:21]
	v_pk_add_f32 v[92:93], v[92:93], v[22:23]
	v_pk_add_f32 v[94:95], v[94:95], v[24:25]
	global_store_dwordx4 v[206:207], v[88:91], off
	global_store_dwordx4 v[206:207], v[92:95], off offset:16
	ds_read_b128 v[10:13], v208 offset:16896
	v_lshl_add_u64 v[206:207], v[204:205], 0, s[20:21]
	s_add_u32 s20, s20, 0x20000
	s_waitcnt lgkmcnt(0)
	v_lshlrev_b32_e32 v18, 16, v10
	v_and_b32_e32 v19, 0xffff0000, v10
	v_lshlrev_b32_e32 v20, 16, v11
	v_and_b32_e32 v21, 0xffff0000, v11
	v_lshlrev_b32_e32 v22, 16, v12
	v_and_b32_e32 v23, 0xffff0000, v12
	v_lshlrev_b32_e32 v24, 16, v13
	v_and_b32_e32 v25, 0xffff0000, v13
	s_waitcnt vmcnt(30)
	v_pk_add_f32 v[96:97], v[96:97], v[18:19]
	v_pk_add_f32 v[98:99], v[98:99], v[20:21]
	v_pk_add_f32 v[100:101], v[100:101], v[22:23]
	v_pk_add_f32 v[102:103], v[102:103], v[24:25]
	global_store_dwordx4 v[206:207], v[96:99], off
	global_store_dwordx4 v[206:207], v[100:103], off offset:16
	ds_read_b128 v[10:13], v208 offset:25344
	v_lshl_add_u64 v[206:207], v[204:205], 0, s[20:21]
	s_add_u32 s20, s20, 0x20000
	s_waitcnt lgkmcnt(0)
	v_lshlrev_b32_e32 v18, 16, v10
	v_and_b32_e32 v19, 0xffff0000, v10
	v_lshlrev_b32_e32 v20, 16, v11
	v_and_b32_e32 v21, 0xffff0000, v11
	v_lshlrev_b32_e32 v22, 16, v12
	v_and_b32_e32 v23, 0xffff0000, v12
	v_lshlrev_b32_e32 v24, 16, v13
	v_and_b32_e32 v25, 0xffff0000, v13
	s_waitcnt vmcnt(30)
	v_pk_add_f32 v[104:105], v[104:105], v[18:19]
	v_pk_add_f32 v[106:107], v[106:107], v[20:21]
	v_pk_add_f32 v[108:109], v[108:109], v[22:23]
	v_pk_add_f32 v[110:111], v[110:111], v[24:25]
	global_store_dwordx4 v[206:207], v[104:107], off
	global_store_dwordx4 v[206:207], v[108:111], off offset:16
	ds_read_b128 v[10:13], v208 offset:33792
	v_lshl_add_u64 v[206:207], v[204:205], 0, s[20:21]
	s_add_u32 s20, s20, 0x20000
	s_waitcnt lgkmcnt(0)
	v_lshlrev_b32_e32 v18, 16, v10
	v_and_b32_e32 v19, 0xffff0000, v10
	v_lshlrev_b32_e32 v20, 16, v11
	v_and_b32_e32 v21, 0xffff0000, v11
	v_lshlrev_b32_e32 v22, 16, v12
	v_and_b32_e32 v23, 0xffff0000, v12
	v_lshlrev_b32_e32 v24, 16, v13
	v_and_b32_e32 v25, 0xffff0000, v13
	s_waitcnt vmcnt(30)
	v_pk_add_f32 v[112:113], v[112:113], v[18:19]
	v_pk_add_f32 v[114:115], v[114:115], v[20:21]
	v_pk_add_f32 v[116:117], v[116:117], v[22:23]
	v_pk_add_f32 v[118:119], v[118:119], v[24:25]
	global_store_dwordx4 v[206:207], v[112:115], off
	global_store_dwordx4 v[206:207], v[116:119], off offset:16
	ds_read_b128 v[10:13], v208 offset:42240
	v_lshl_add_u64 v[206:207], v[204:205], 0, s[20:21]
	s_add_u32 s20, s20, 0x20000
	s_waitcnt lgkmcnt(0)
	v_lshlrev_b32_e32 v18, 16, v10
	v_and_b32_e32 v19, 0xffff0000, v10
	v_lshlrev_b32_e32 v20, 16, v11
	v_and_b32_e32 v21, 0xffff0000, v11
	v_lshlrev_b32_e32 v22, 16, v12
	v_and_b32_e32 v23, 0xffff0000, v12
	v_lshlrev_b32_e32 v24, 16, v13
	v_and_b32_e32 v25, 0xffff0000, v13
	s_waitcnt vmcnt(30)
	v_pk_add_f32 v[120:121], v[120:121], v[18:19]
	v_pk_add_f32 v[122:123], v[122:123], v[20:21]
	v_pk_add_f32 v[124:125], v[124:125], v[22:23]
	v_pk_add_f32 v[126:127], v[126:127], v[24:25]
	global_store_dwordx4 v[206:207], v[120:123], off
	global_store_dwordx4 v[206:207], v[124:127], off offset:16
	ds_read_b128 v[10:13], v208 offset:50688
	v_lshl_add_u64 v[206:207], v[204:205], 0, s[20:21]
	s_add_u32 s20, s20, 0x20000
	s_waitcnt lgkmcnt(0)
	v_lshlrev_b32_e32 v18, 16, v10
	v_and_b32_e32 v19, 0xffff0000, v10
	v_lshlrev_b32_e32 v20, 16, v11
	v_and_b32_e32 v21, 0xffff0000, v11
	v_lshlrev_b32_e32 v22, 16, v12
	v_and_b32_e32 v23, 0xffff0000, v12
	v_lshlrev_b32_e32 v24, 16, v13
	v_and_b32_e32 v25, 0xffff0000, v13
	s_waitcnt vmcnt(30)
	v_pk_add_f32 v[210:211], v[210:211], v[18:19]
	v_pk_add_f32 v[212:213], v[212:213], v[20:21]
	v_pk_add_f32 v[214:215], v[214:215], v[22:23]
	v_pk_add_f32 v[216:217], v[216:217], v[24:25]
	global_store_dwordx4 v[206:207], v[210:213], off
	global_store_dwordx4 v[206:207], v[214:217], off offset:16
	ds_read_b128 v[10:13], v208 offset:59136
	v_lshl_add_u64 v[206:207], v[204:205], 0, s[20:21]
	s_add_u32 s20, s20, 0x20000
	s_waitcnt lgkmcnt(0)
	v_lshlrev_b32_e32 v18, 16, v10
	v_and_b32_e32 v19, 0xffff0000, v10
	v_lshlrev_b32_e32 v20, 16, v11
	v_and_b32_e32 v21, 0xffff0000, v11
	v_lshlrev_b32_e32 v22, 16, v12
	v_and_b32_e32 v23, 0xffff0000, v12
	v_lshlrev_b32_e32 v24, 16, v13
	v_and_b32_e32 v25, 0xffff0000, v13
	s_waitcnt vmcnt(30)
	v_pk_add_f32 v[218:219], v[218:219], v[18:19]
	v_pk_add_f32 v[220:221], v[220:221], v[20:21]
	v_pk_add_f32 v[226:227], v[226:227], v[22:23]
	v_pk_add_f32 v[228:229], v[228:229], v[24:25]
	global_store_dwordx4 v[206:207], v[218:221], off
	global_store_dwordx4 v[206:207], v[226:229], off offset:16
	v_readlane_b32 s0, v254, 6
	v_readlane_b32 s1, v254, 7
	s_add_i32 s51, s51, s0
	s_add_i32 s52, s52, s1
	s_add_i32 s50, s50, s0
	s_cmp_ge_i32 s51, s8
	s_barrier
	s_cbranch_scc0 .LBB0_299
	v_readlane_b32 s33, v254, 35
	s_mov_b32 s34, 0x18000
	v_mov_b32_e32 v233, 1.0
